# all 8 GEMM epilogues: non-temporal hint on the output stores (128 sites)
# baseline (speedup 1.0000x reference)
; __device__ __forceinline__ unsigned pk2(float lo, float hi) { f32x2 v = {lo, hi}; bf16x2_t b = __builtin_convertvector(v, bf16x2_t); return __builtin_bit_cast(unsigned, b); }
;     __device__ __forceinline__ void operator()(const f32x4 (&acc)[2][2][4][2], const Unit& u, int wr, int wc, int fr, int fq) const {
;         const int row0 = u.pm * BM + wr * 64 + fr; const int col0 = u.pn * BM + wc * 32 + 8 * fq;
; #pragma unroll
;         for (int ai = 0; ai < 2; ++ai)
; #pragma unroll
;             for (int m = 0; m < 4; ++m) { const int row = row0 + ai * HALF + m * 16; const float rb = rowbias ? rowbias[row] : 0.f; bf16_t* rowp = O + (size_t)row * ldc + col0;
; #pragma unroll
;                 for (int bj = 0; bj < 2; ++bj) { const f32x4 v0 = acc[ai][bj][m][0] + rb, v1 = acc[ai][bj][m][1] + rb;
;                     u32x4 w; w.x = pk2(v0[0], v0[1]); w.y = pk2(v0[2], v0[3]); w.z = pk2(v1[0], v1[1]); w.w = pk2(v1[2], v1[3]);
;                     *(u32x4*)(rowp + bj * HALF) = w; } }
.LBB0_384:
	s_mov_b32 s60, 1
	v_lshl_or_b32 v146, s79, 8, v150
	v_lshl_add_u32 v155, s40, 8, v148
	v_ashrrev_i32_e32 v147, 31, v146
	v_mov_b64_e32 v[144:145], s[8:9]
	v_mad_i64_i32 v[156:157], s[42:43], v155, s78, v[144:145]
	v_lshlrev_b64 v[146:147], 1, v[146:147]
	v_pk_add_f32 v[126:127], v[126:127], 0 op_sel_hi:[1,0]
	v_pk_add_f32 v[124:125], v[124:125], 0 op_sel_hi:[1,0]
	v_pk_add_f32 v[158:159], v[122:123], 0 op_sel_hi:[1,0]
	v_pk_add_f32 v[122:123], v[120:121], 0 op_sel_hi:[1,0]
	v_lshl_add_u64 v[156:157], v[156:157], 0, v[146:147]
	v_cvt_pk_bf16_f32 v120, v124, v125
	v_cvt_pk_bf16_f32 v121, v126, v127
	v_cvt_pk_bf16_f32 v122, v122, v123
	v_cvt_pk_bf16_f32 v123, v158, v159
	global_store_dwordx4 v[156:157], v[120:123], off nt
	v_pk_add_f32 v[114:115], v[114:115], 0 op_sel_hi:[1,0]
	v_pk_add_f32 v[112:113], v[112:113], 0 op_sel_hi:[1,0]
	v_pk_add_f32 v[120:121], v[106:107], 0 op_sel_hi:[1,0]
	v_pk_add_f32 v[106:107], v[104:105], 0 op_sel_hi:[1,0]
	v_cvt_pk_bf16_f32 v104, v112, v113
	v_cvt_pk_bf16_f32 v105, v114, v115
	v_cvt_pk_bf16_f32 v106, v106, v107
	v_cvt_pk_bf16_f32 v107, v120, v121
	global_store_dwordx4 v[156:157], v[104:107], off offset:256 nt
	v_pk_add_f32 v[110:111], v[110:111], 0 op_sel_hi:[1,0]
	v_pk_add_f32 v[108:109], v[108:109], 0 op_sel_hi:[1,0]
	v_or_b32_e32 v104, 16, v155
	v_mad_i64_i32 v[104:105], s[42:43], v104, s78, v[144:145]
	v_lshl_add_u64 v[112:113], v[104:105], 0, v[146:147]
	v_pk_add_f32 v[106:107], v[118:119], 0 op_sel_hi:[1,0]
	v_pk_add_f32 v[104:105], v[116:117], 0 op_sel_hi:[1,0]
	v_pk_add_f32 v[98:99], v[98:99], 0 op_sel_hi:[1,0]
	v_cvt_pk_bf16_f32 v104, v104, v105
	v_cvt_pk_bf16_f32 v105, v106, v107
	v_cvt_pk_bf16_f32 v106, v108, v109
	v_cvt_pk_bf16_f32 v107, v110, v111
	global_store_dwordx4 v[112:113], v[104:107], off nt
	v_pk_add_f32 v[96:97], v[96:97], 0 op_sel_hi:[1,0]
	v_pk_add_f32 v[94:95], v[94:95], 0 op_sel_hi:[1,0]
	v_pk_add_f32 v[104:105], v[90:91], 0 op_sel_hi:[1,0]
	v_pk_add_f32 v[90:91], v[88:89], 0 op_sel_hi:[1,0]
	v_cvt_pk_bf16_f32 v88, v96, v97
	v_cvt_pk_bf16_f32 v89, v98, v99
	v_cvt_pk_bf16_f32 v90, v90, v91
	v_cvt_pk_bf16_f32 v91, v104, v105
	global_store_dwordx4 v[112:113], v[88:91], off offset:256 nt
	v_pk_add_f32 v[92:93], v[92:93], 0 op_sel_hi:[1,0]
	v_pk_add_f32 v[82:83], v[82:83], 0 op_sel_hi:[1,0]
	v_or_b32_e32 v88, 32, v155
	v_mad_i64_i32 v[88:89], s[42:43], v88, s78, v[144:145]
	v_lshl_add_u64 v[96:97], v[88:89], 0, v[146:147]
	v_pk_add_f32 v[90:91], v[102:103], 0 op_sel_hi:[1,0]
	v_pk_add_f32 v[88:89], v[100:101], 0 op_sel_hi:[1,0]
	v_pk_add_f32 v[80:81], v[80:81], 0 op_sel_hi:[1,0]
	v_cvt_pk_bf16_f32 v88, v88, v89
	v_cvt_pk_bf16_f32 v89, v90, v91
	v_cvt_pk_bf16_f32 v90, v92, v93
	v_cvt_pk_bf16_f32 v91, v94, v95
	global_store_dwordx4 v[96:97], v[88:91], off nt
	v_pk_add_f32 v[78:79], v[78:79], 0 op_sel_hi:[1,0]
	v_pk_add_f32 v[76:77], v[76:77], 0 op_sel_hi:[1,0]
	v_pk_add_f32 v[88:89], v[74:75], 0 op_sel_hi:[1,0]
	v_pk_add_f32 v[74:75], v[72:73], 0 op_sel_hi:[1,0]
	v_cvt_pk_bf16_f32 v72, v80, v81
	v_cvt_pk_bf16_f32 v73, v82, v83
	v_cvt_pk_bf16_f32 v74, v74, v75
	v_cvt_pk_bf16_f32 v75, v88, v89
	global_store_dwordx4 v[96:97], v[72:75], off offset:256 nt
	v_pk_add_f32 v[70:71], v[70:71], 0 op_sel_hi:[1,0]
	v_pk_add_f32 v[68:69], v[68:69], 0 op_sel_hi:[1,0]
	v_or_b32_e32 v72, 48, v155
	v_mad_i64_i32 v[72:73], s[42:43], v72, s78, v[144:145]
	v_lshl_add_u64 v[80:81], v[72:73], 0, v[146:147]
	v_pk_add_f32 v[74:75], v[86:87], 0 op_sel_hi:[1,0]
	v_pk_add_f32 v[72:73], v[84:85], 0 op_sel_hi:[1,0]
	v_pk_add_f32 v[62:63], v[62:63], 0 op_sel_hi:[1,0]
	v_cvt_pk_bf16_f32 v72, v72, v73
	v_cvt_pk_bf16_f32 v73, v74, v75
	v_cvt_pk_bf16_f32 v74, v76, v77
	v_cvt_pk_bf16_f32 v75, v78, v79
	global_store_dwordx4 v[80:81], v[72:75], off nt
	v_pk_add_f32 v[60:61], v[60:61], 0 op_sel_hi:[1,0]
	v_pk_add_f32 v[50:51], v[50:51], 0 op_sel_hi:[1,0]
	v_pk_add_f32 v[72:73], v[66:67], 0 op_sel_hi:[1,0]
; __device__ __forceinline__ unsigned pk2(float lo, float hi) { f32x2 v = {lo, hi}; bf16x2_t b = __builtin_convertvector(v, bf16x2_t); return __builtin_bit_cast(unsigned, b); }
;     __device__ __forceinline__ void operator()(const f32x4 (&acc)[2][2][4][2], const Unit& u, int wr, int wc, int fr, int fq) const {
;         const int row0 = u.pm * BM + wr * 64 + fr; const int col0 = u.pn * BM + wc * 32 + 8 * fq;
; #pragma unroll
;         for (int ai = 0; ai < 2; ++ai)
; #pragma unroll
;             for (int m = 0; m < 4; ++m) { const int row = row0 + ai * HALF + m * 16; const float rb = rowbias ? rowbias[row] : 0.f; bf16_t* rowp = O + (size_t)row * ldc + col0;
; #pragma unroll
;                 for (int bj = 0; bj < 2; ++bj) { const f32x4 v0 = acc[ai][bj][m][0] + rb, v1 = acc[ai][bj][m][1] + rb;
;                     u32x4 w; w.x = pk2(v0[0], v0[1]); w.y = pk2(v0[2], v0[3]); w.z = pk2(v1[0], v1[1]); w.w = pk2(v1[2], v1[3]);
;                     *(u32x4*)(rowp + bj * HALF) = w; } }
	v_pk_add_f32 v[66:67], v[64:65], 0 op_sel_hi:[1,0]
	v_cvt_pk_bf16_f32 v64, v68, v69
	v_cvt_pk_bf16_f32 v65, v70, v71
	v_cvt_pk_bf16_f32 v66, v66, v67
	v_cvt_pk_bf16_f32 v67, v72, v73
	global_store_dwordx4 v[80:81], v[64:67], off offset:256 nt
	v_pk_add_f32 v[48:49], v[48:49], 0 op_sel_hi:[1,0]
	v_pk_add_f32 v[46:47], v[46:47], 0 op_sel_hi:[1,0]
	v_add_u32_e32 v64, 0x80, v155
	v_mad_i64_i32 v[64:65], s[42:43], v64, s78, v[144:145]
	v_pk_add_f32 v[66:67], v[58:59], 0 op_sel_hi:[1,0]
	v_pk_add_f32 v[58:59], v[56:57], 0 op_sel_hi:[1,0]
	v_lshl_add_u64 v[64:65], v[64:65], 0, v[146:147]
	v_cvt_pk_bf16_f32 v56, v60, v61
	v_cvt_pk_bf16_f32 v57, v62, v63
	v_cvt_pk_bf16_f32 v58, v58, v59
	v_cvt_pk_bf16_f32 v59, v66, v67
	global_store_dwordx4 v[64:65], v[56:59], off nt
	v_pk_add_f32 v[44:45], v[44:45], 0 op_sel_hi:[1,0]
	v_pk_add_f32 v[34:35], v[34:35], 0 op_sel_hi:[1,0]
	v_pk_add_f32 v[56:57], v[42:43], 0 op_sel_hi:[1,0]
	v_pk_add_f32 v[42:43], v[40:41], 0 op_sel_hi:[1,0]
	v_cvt_pk_bf16_f32 v40, v48, v49
	v_cvt_pk_bf16_f32 v41, v50, v51
	v_cvt_pk_bf16_f32 v42, v42, v43
	v_cvt_pk_bf16_f32 v43, v56, v57
	global_store_dwordx4 v[64:65], v[40:43], off offset:256 nt
	v_pk_add_f32 v[32:33], v[32:33], 0 op_sel_hi:[1,0]
	v_pk_add_f32 v[30:31], v[30:31], 0 op_sel_hi:[1,0]
	v_add_u32_e32 v40, 0x90, v155
	v_mad_i64_i32 v[40:41], s[42:43], v40, s78, v[144:145]
	v_lshl_add_u64 v[48:49], v[40:41], 0, v[146:147]
	v_pk_add_f32 v[42:43], v[54:55], 0 op_sel_hi:[1,0]
	v_pk_add_f32 v[40:41], v[52:53], 0 op_sel_hi:[1,0]
	v_pk_add_f32 v[28:29], v[28:29], 0 op_sel_hi:[1,0]
	v_cvt_pk_bf16_f32 v40, v40, v41
	v_cvt_pk_bf16_f32 v41, v42, v43
	v_cvt_pk_bf16_f32 v42, v44, v45
	v_cvt_pk_bf16_f32 v43, v46, v47
	global_store_dwordx4 v[48:49], v[40:43], off nt
	v_pk_add_f32 v[18:19], v[18:19], 0 op_sel_hi:[1,0]
	v_pk_add_f32 v[16:17], v[16:17], 0 op_sel_hi:[1,0]
	v_pk_add_f32 v[40:41], v[26:27], 0 op_sel_hi:[1,0]
	v_pk_add_f32 v[26:27], v[24:25], 0 op_sel_hi:[1,0]
	v_cvt_pk_bf16_f32 v24, v32, v33
	v_cvt_pk_bf16_f32 v25, v34, v35
	v_cvt_pk_bf16_f32 v26, v26, v27
	v_cvt_pk_bf16_f32 v27, v40, v41
	global_store_dwordx4 v[48:49], v[24:27], off offset:256 nt
	v_pk_add_f32 v[14:15], v[14:15], 0 op_sel_hi:[1,0]
	v_pk_add_f32 v[12:13], v[12:13], 0 op_sel_hi:[1,0]
	v_add_u32_e32 v24, 0xa0, v155
	v_mad_i64_i32 v[24:25], s[42:43], v24, s78, v[144:145]
	v_lshl_add_u64 v[32:33], v[24:25], 0, v[146:147]
	v_pk_add_f32 v[26:27], v[38:39], 0 op_sel_hi:[1,0]
	v_pk_add_f32 v[24:25], v[36:37], 0 op_sel_hi:[1,0]
	v_pk_add_f32 v[6:7], v[6:7], 0 op_sel_hi:[1,0]
	v_cvt_pk_bf16_f32 v24, v24, v25
	v_cvt_pk_bf16_f32 v25, v26, v27
	v_cvt_pk_bf16_f32 v26, v28, v29
	v_cvt_pk_bf16_f32 v27, v30, v31
	global_store_dwordx4 v[32:33], v[24:27], off nt
	v_pk_add_f32 v[4:5], v[4:5], 0 op_sel_hi:[1,0]
	s_andn2_b64 vcc, exec, s[0:1]
	v_pk_add_f32 v[24:25], v[10:11], 0 op_sel_hi:[1,0]
	v_pk_add_f32 v[10:11], v[8:9], 0 op_sel_hi:[1,0]
	v_cvt_pk_bf16_f32 v8, v16, v17
	v_cvt_pk_bf16_f32 v9, v18, v19
	v_cvt_pk_bf16_f32 v10, v10, v11
	v_cvt_pk_bf16_f32 v11, v24, v25
	global_store_dwordx4 v[32:33], v[8:11], off offset:256 nt
	s_mov_b64 s[0:1], -1
	s_nop 0
	v_add_u32_e32 v8, 0xb0, v155
	v_mad_i64_i32 v[8:9], s[42:43], v8, s78, v[144:145]
	v_lshl_add_u64 v[16:17], v[8:9], 0, v[146:147]
	v_pk_add_f32 v[10:11], v[22:23], 0 op_sel_hi:[1,0]
	v_pk_add_f32 v[8:9], v[20:21], 0 op_sel_hi:[1,0]
	s_nop 0
	v_cvt_pk_bf16_f32 v8, v8, v9
	v_cvt_pk_bf16_f32 v9, v10, v11
	v_cvt_pk_bf16_f32 v10, v12, v13
	v_cvt_pk_bf16_f32 v11, v14, v15
	global_store_dwordx4 v[16:17], v[8:11], off nt
	s_nop 1
	v_pk_add_f32 v[8:9], v[2:3], 0 op_sel_hi:[1,0]
	v_pk_add_f32 v[2:3], v[0:1], 0 op_sel_hi:[1,0]
	v_cvt_pk_bf16_f32 v0, v4, v5
	v_cvt_pk_bf16_f32 v1, v6, v7
	v_cvt_pk_bf16_f32 v2, v2, v3
	v_cvt_pk_bf16_f32 v3, v8, v9
	global_store_dwordx4 v[16:17], v[0:3], off offset:256 nt
	s_cbranch_vccnz .LBB0_377
	s_andn2_b64 vcc, exec, s[6:7]
	s_cbranch_vccnz .LBB0_376
	s_barrier
	s_branch .LBB0_376

; __device__ __forceinline__ unsigned pk2(float lo, float hi) { f32x2 v = {lo, hi}; bf16x2_t b = __builtin_convertvector(v, bf16x2_t); return __builtin_bit_cast(unsigned, b); }
;     __device__ __forceinline__ void operator()(const f32x4 (&acc)[2][2][4][2], const Unit& u, int wr, int wc, int fr, int fq) const {
;         const int row0 = u.pm * BM + wr * 64 + fr; const int col0 = u.pn * BM + wc * 32 + 8 * fq;
;         const float* gp = gate + (size_t)(u.pm >> 5) * 6144;
; #pragma unroll
;         for (int bj = 0; bj < 2; ++bj) { const int c = col0 + bj * HALF;
;             const f32x4 g0 = *(const f32x4*)(gp + c), g1 = *(const f32x4*)(gp + c + 4);
;             const f32x4 b0 = bias ? *(const f32x4*)(bias + c) : (f32x4){0.f, 0.f, 0.f, 0.f}, b1 = bias ? *(const f32x4*)(bias + c + 4) : (f32x4){0.f, 0.f, 0.f, 0.f};
; #pragma unroll
;             for (int ai = 0; ai < 2; ++ai)
; #pragma unroll
;                 for (int m = 0; m < 4; ++m) { const size_t off = (size_t)(row0 + ai * HALF + m * 16) * 1024 + c;
;                     f32x4 x0, x1;
;                     if (BASE_BF16) { const u32x4 v = *(const u32x4*)((const bf16_t*)base + off);
;                         x0 = (f32x4){__uint_as_float(v.x << 16), __uint_as_float(v.x & 0xffff0000u), __uint_as_float(v.y << 16), __uint_as_float(v.y & 0xffff0000u)};
;                         x1 = (f32x4){__uint_as_float(v.z << 16), __uint_as_float(v.z & 0xffff0000u), __uint_as_float(v.w << 16), __uint_as_float(v.w & 0xffff0000u)}; }
;                     else { x0 = *(const f32x4*)((const float*)base + off); x1 = *(const f32x4*)((const float*)base + off + 4); }
;                     x0 = x0 + g0 * (acc[ai][bj][m][0] + b0); x1 = x1 + g1 * (acc[ai][bj][m][1] + b1);
;                     if (OUT_BF16) { u32x4 w; w.x = pk2(x0[0], x0[1]); w.y = pk2(x0[2], x0[3]); w.z = pk2(x1[0], x1[1]); w.w = pk2(x1[2], x1[3]); *(u32x4*)((bf16_t*)out + off) = w; }
;                     else { *(f32x4*)((float*)out + off) = x0; *(f32x4*)((float*)out + off + 4) = x1; } } }
.LBB0_593:
	v_lshl_add_u32 v176, s52, 8, v162
	v_lshl_or_b32 v154, s83, 8, v164
	s_ashr_i32 s33, s52, 5
	v_ashrrev_i32_e32 v177, 31, v176
	s_mul_hi_i32 s34, s33, 0x6000
	s_mulk_i32 s33, 0x6000
	v_lshlrev_b64 v[156:157], 10, v[176:177]
	v_ashrrev_i32_e32 v155, 31, v154
	s_add_u32 s54, s76, s33
	v_lshl_add_u64 v[178:179], v[156:157], 0, v[154:155]
	s_addc_u32 s55, s77, s34
	v_lshl_add_u64 v[160:161], v[178:179], 2, s[36:37]
	v_lshl_add_u64 v[158:159], v[154:155], 2, s[54:55]
	global_load_dwordx4 v[168:171], v[160:161], off
	global_load_dwordx4 v[132:135], v[158:159], off
	global_load_dwordx4 v[128:131], v[158:159], off offset:16
	global_load_dwordx4 v[172:175], v[160:161], off offset:16
	v_pk_add_f32 v[182:183], v[120:121], 0 op_sel_hi:[1,0]
	v_or_b32_e32 v120, 16, v176
	v_pk_add_f32 v[126:127], v[126:127], 0 op_sel_hi:[1,0]
	v_pk_add_f32 v[124:125], v[124:125], 0 op_sel_hi:[1,0]
	v_pk_add_f32 v[180:181], v[122:123], 0 op_sel_hi:[1,0]
	v_ashrrev_i32_e32 v121, 31, v120
	v_lshlrev_b64 v[120:121], 10, v[120:121]
	v_lshl_add_u64 v[178:179], v[178:179], 1, s[8:9]
	v_lshl_add_u64 v[184:185], v[120:121], 0, v[154:155]
	v_lshl_add_u64 v[122:123], v[184:185], 2, s[36:37]
	v_pk_add_f32 v[118:119], v[118:119], 0 op_sel_hi:[1,0]
	v_pk_add_f32 v[116:117], v[116:117], 0 op_sel_hi:[1,0]
	v_pk_add_f32 v[110:111], v[110:111], 0 op_sel_hi:[1,0]
	v_pk_add_f32 v[108:109], v[108:109], 0 op_sel_hi:[1,0]
	v_pk_add_f32 v[102:103], v[102:103], 0 op_sel_hi:[1,0]
	v_pk_add_f32 v[100:101], v[100:101], 0 op_sel_hi:[1,0]
	v_pk_add_f32 v[94:95], v[94:95], 0 op_sel_hi:[1,0]
	v_pk_add_f32 v[92:93], v[92:93], 0 op_sel_hi:[1,0]
	v_pk_add_f32 v[86:87], v[86:87], 0 op_sel_hi:[1,0]
	v_pk_add_f32 v[84:85], v[84:85], 0 op_sel_hi:[1,0]
	v_pk_add_f32 v[78:79], v[78:79], 0 op_sel_hi:[1,0]
	v_pk_add_f32 v[76:77], v[76:77], 0 op_sel_hi:[1,0]
	v_pk_add_f32 v[66:67], v[66:67], 0 op_sel_hi:[1,0]
	v_pk_add_f32 v[64:65], v[64:65], 0 op_sel_hi:[1,0]
	v_pk_add_f32 v[58:59], v[58:59], 0 op_sel_hi:[1,0]
	v_pk_add_f32 v[56:57], v[56:57], 0 op_sel_hi:[1,0]
	v_pk_add_f32 v[70:71], v[70:71], 0 op_sel_hi:[1,0]
	v_pk_add_f32 v[68:69], v[68:69], 0 op_sel_hi:[1,0]
	v_pk_add_f32 v[62:63], v[62:63], 0 op_sel_hi:[1,0]
	v_pk_add_f32 v[54:55], v[54:55], 0 op_sel_hi:[1,0]
	v_pk_add_f32 v[52:53], v[52:53], 0 op_sel_hi:[1,0]
	v_pk_add_f32 v[50:51], v[50:51], 0 op_sel_hi:[1,0]
	v_pk_add_f32 v[48:49], v[48:49], 0 op_sel_hi:[1,0]
	v_pk_add_f32 v[46:47], v[46:47], 0 op_sel_hi:[1,0]
	v_pk_add_f32 v[44:45], v[44:45], 0 op_sel_hi:[1,0]
	v_pk_add_f32 v[42:43], v[42:43], 0 op_sel_hi:[1,0]
	v_pk_add_f32 v[40:41], v[40:41], 0 op_sel_hi:[1,0]
	v_pk_add_f32 v[38:39], v[38:39], 0 op_sel_hi:[1,0]
	v_pk_add_f32 v[36:37], v[36:37], 0 op_sel_hi:[1,0]
	v_pk_add_f32 v[34:35], v[34:35], 0 op_sel_hi:[1,0]
	v_pk_add_f32 v[32:33], v[32:33], 0 op_sel_hi:[1,0]
	v_pk_add_f32 v[30:31], v[30:31], 0 op_sel_hi:[1,0]
	v_pk_add_f32 v[28:29], v[28:29], 0 op_sel_hi:[1,0]
	v_pk_add_f32 v[26:27], v[26:27], 0 op_sel_hi:[1,0]
	v_pk_add_f32 v[24:25], v[24:25], 0 op_sel_hi:[1,0]
	v_pk_add_f32 v[22:23], v[22:23], 0 op_sel_hi:[1,0]
	v_pk_add_f32 v[20:21], v[20:21], 0 op_sel_hi:[1,0]
	v_pk_add_f32 v[18:19], v[18:19], 0 op_sel_hi:[1,0]
	v_pk_add_f32 v[16:17], v[16:17], 0 op_sel_hi:[1,0]
	v_pk_add_f32 v[14:15], v[14:15], 0 op_sel_hi:[1,0]
	v_pk_add_f32 v[12:13], v[12:13], 0 op_sel_hi:[1,0]
	v_pk_add_f32 v[10:11], v[10:11], 0 op_sel_hi:[1,0]
	v_pk_add_f32 v[8:9], v[8:9], 0 op_sel_hi:[1,0]
	v_pk_add_f32 v[6:7], v[6:7], 0 op_sel_hi:[1,0]
	v_pk_add_f32 v[4:5], v[4:5], 0 op_sel_hi:[1,0]
	v_pk_add_f32 v[2:3], v[2:3], 0 op_sel_hi:[1,0]
	v_pk_add_f32 v[0:1], v[0:1], 0 op_sel_hi:[1,0]
	s_andn2_b64 vcc, exec, s[0:1]
	s_mov_b64 s[0:1], -1
	s_waitcnt vmcnt(0)
	v_pk_fma_f32 v[126:127], v[126:127], v[134:135], v[170:171]
	v_pk_fma_f32 v[124:125], v[124:125], v[132:133], v[168:169]
	v_pk_fma_f32 v[168:169], v[180:181], v[130:131], v[174:175]
	v_pk_fma_f32 v[170:171], v[182:183], v[128:129], v[172:173]
	v_cvt_pk_bf16_f32 v124, v124, v125
	v_cvt_pk_bf16_f32 v125, v126, v127
	v_cvt_pk_bf16_f32 v126, v170, v171
	v_cvt_pk_bf16_f32 v127, v168, v169
	global_store_dwordx4 v[178:179], v[124:127], off nt
	global_load_dwordx4 v[124:127], v[122:123], off
	s_nop 0
	global_load_dwordx4 v[168:171], v[122:123], off offset:16
	v_pk_add_f32 v[174:175], v[112:113], 0 op_sel_hi:[1,0]
	v_or_b32_e32 v112, 32, v176
	v_pk_add_f32 v[172:173], v[114:115], 0 op_sel_hi:[1,0]
	v_ashrrev_i32_e32 v113, 31, v112
	v_lshlrev_b64 v[112:113], 10, v[112:113]
	v_lshl_add_u64 v[178:179], v[112:113], 0, v[154:155]
	v_lshl_add_u64 v[180:181], v[184:185], 1, s[8:9]
	v_lshl_add_u64 v[114:115], v[178:179], 2, s[36:37]
	s_waitcnt vmcnt(1)
	v_pk_fma_f32 v[118:119], v[118:119], v[134:135], v[126:127]
	v_pk_fma_f32 v[116:117], v[116:117], v[132:133], v[124:125]
	s_waitcnt vmcnt(0)
	v_pk_fma_f32 v[124:125], v[172:173], v[130:131], v[170:171]
	v_pk_fma_f32 v[126:127], v[174:175], v[128:129], v[168:169]
	v_cvt_pk_bf16_f32 v116, v116, v117
	v_cvt_pk_bf16_f32 v117, v118, v119
	v_cvt_pk_bf16_f32 v118, v126, v127
	v_cvt_pk_bf16_f32 v119, v124, v125
	global_store_dwordx4 v[180:181], v[116:119], off nt
	global_load_dwordx4 v[116:119], v[114:115], off
	s_nop 0
	global_load_dwordx4 v[124:127], v[114:115], off offset:16
	v_pk_add_f32 v[170:171], v[104:105], 0 op_sel_hi:[1,0]
	v_or_b32_e32 v104, 48, v176
	v_pk_add_f32 v[168:169], v[106:107], 0 op_sel_hi:[1,0]
	v_ashrrev_i32_e32 v105, 31, v104
	v_lshlrev_b64 v[104:105], 10, v[104:105]
	v_lshl_add_u64 v[172:173], v[104:105], 0, v[154:155]
	v_lshl_add_u64 v[174:175], v[178:179], 1, s[8:9]
	v_lshl_add_u64 v[106:107], v[172:173], 2, s[36:37]
	s_waitcnt vmcnt(1)
; __device__ __forceinline__ unsigned pk2(float lo, float hi) { f32x2 v = {lo, hi}; bf16x2_t b = __builtin_convertvector(v, bf16x2_t); return __builtin_bit_cast(unsigned, b); }
;     __device__ __forceinline__ void operator()(const f32x4 (&acc)[2][2][4][2], const Unit& u, int wr, int wc, int fr, int fq) const {
;     ...
;         for (int bj = 0; bj < 2; ++bj) { const int c = col0 + bj * HALF;
;             const f32x4 g0 = *(const f32x4*)(gp + c), g1 = *(const f32x4*)(gp + c + 4);
;             const f32x4 b0 = bias ? *(const f32x4*)(bias + c) : (f32x4){0.f, 0.f, 0.f, 0.f}, b1 = bias ? *(const f32x4*)(bias + c + 4) : (f32x4){0.f, 0.f, 0.f, 0.f};
; #pragma unroll
;             for (int ai = 0; ai < 2; ++ai)
; #pragma unroll
;                 for (int m = 0; m < 4; ++m) { const size_t off = (size_t)(row0 + ai * HALF + m * 16) * 1024 + c;
;                     f32x4 x0, x1;
;                     if (BASE_BF16) { const u32x4 v = *(const u32x4*)((const bf16_t*)base + off);
;                         x0 = (f32x4){__uint_as_float(v.x << 16), __uint_as_float(v.x & 0xffff0000u), __uint_as_float(v.y << 16), __uint_as_float(v.y & 0xffff0000u)};
;                         x1 = (f32x4){__uint_as_float(v.z << 16), __uint_as_float(v.z & 0xffff0000u), __uint_as_float(v.w << 16), __uint_as_float(v.w & 0xffff0000u)}; }
;                     else { x0 = *(const f32x4*)((const float*)base + off); x1 = *(const f32x4*)((const float*)base + off + 4); }
;                     x0 = x0 + g0 * (acc[ai][bj][m][0] + b0); x1 = x1 + g1 * (acc[ai][bj][m][1] + b1);
;                     if (OUT_BF16) { u32x4 w; w.x = pk2(x0[0], x0[1]); w.y = pk2(x0[2], x0[3]); w.z = pk2(x1[0], x1[1]); w.w = pk2(x1[2], x1[3]); *(u32x4*)((bf16_t*)out + off) = w; }
;                     else { *(f32x4*)((float*)out + off) = x0; *(f32x4*)((float*)out + off + 4) = x1; } } }
	v_pk_fma_f32 v[110:111], v[110:111], v[134:135], v[118:119]
	v_pk_fma_f32 v[108:109], v[108:109], v[132:133], v[116:117]
	s_waitcnt vmcnt(0)
	v_pk_fma_f32 v[116:117], v[168:169], v[130:131], v[126:127]
	v_pk_fma_f32 v[118:119], v[170:171], v[128:129], v[124:125]
	v_cvt_pk_bf16_f32 v108, v108, v109
	v_cvt_pk_bf16_f32 v109, v110, v111
	v_cvt_pk_bf16_f32 v110, v118, v119
	v_cvt_pk_bf16_f32 v111, v116, v117
	global_store_dwordx4 v[174:175], v[108:111], off nt
	global_load_dwordx4 v[108:111], v[106:107], off
	s_nop 0
	global_load_dwordx4 v[116:119], v[106:107], off offset:16
	v_pk_add_f32 v[124:125], v[98:99], 0 op_sel_hi:[1,0]
	v_pk_add_f32 v[126:127], v[96:97], 0 op_sel_hi:[1,0]
	v_lshl_add_u64 v[96:97], v[156:157], 0, s[20:21]
	v_lshl_add_u64 v[168:169], v[96:97], 0, v[154:155]
	v_lshl_add_u64 v[170:171], v[172:173], 1, s[8:9]
	v_lshl_add_u64 v[98:99], v[168:169], 2, s[36:37]
	s_waitcnt vmcnt(1)
	v_pk_fma_f32 v[102:103], v[102:103], v[134:135], v[110:111]
	v_pk_fma_f32 v[100:101], v[100:101], v[132:133], v[108:109]
	s_waitcnt vmcnt(0)
	v_pk_fma_f32 v[108:109], v[124:125], v[130:131], v[118:119]
	v_pk_fma_f32 v[110:111], v[126:127], v[128:129], v[116:117]
	v_cvt_pk_bf16_f32 v100, v100, v101
	v_cvt_pk_bf16_f32 v101, v102, v103
	v_cvt_pk_bf16_f32 v102, v110, v111
	v_cvt_pk_bf16_f32 v103, v108, v109
	global_store_dwordx4 v[170:171], v[100:103], off nt
	global_load_dwordx4 v[100:103], v[98:99], off
	s_nop 0
	global_load_dwordx4 v[108:111], v[98:99], off offset:16
	v_pk_add_f32 v[116:117], v[90:91], 0 op_sel_hi:[1,0]
	v_pk_add_f32 v[118:119], v[88:89], 0 op_sel_hi:[1,0]
	v_lshl_add_u64 v[88:89], v[156:157], 0, s[22:23]
	v_lshl_add_u64 v[124:125], v[88:89], 0, v[154:155]
	v_lshl_add_u64 v[126:127], v[168:169], 1, s[8:9]
	v_lshl_add_u64 v[90:91], v[124:125], 2, s[36:37]
	s_waitcnt vmcnt(1)
	v_pk_fma_f32 v[94:95], v[94:95], v[134:135], v[102:103]
	v_pk_fma_f32 v[92:93], v[92:93], v[132:133], v[100:101]
	s_waitcnt vmcnt(0)
	v_pk_fma_f32 v[100:101], v[116:117], v[130:131], v[110:111]
	v_pk_fma_f32 v[102:103], v[118:119], v[128:129], v[108:109]
	v_cvt_pk_bf16_f32 v92, v92, v93
	v_cvt_pk_bf16_f32 v93, v94, v95
	v_cvt_pk_bf16_f32 v94, v102, v103
	v_cvt_pk_bf16_f32 v95, v100, v101
	global_store_dwordx4 v[126:127], v[92:95], off nt
	global_load_dwordx4 v[92:95], v[90:91], off
	s_nop 0
	global_load_dwordx4 v[100:103], v[90:91], off offset:16
	v_pk_add_f32 v[108:109], v[82:83], 0 op_sel_hi:[1,0]
	v_pk_add_f32 v[110:111], v[80:81], 0 op_sel_hi:[1,0]
	v_lshl_add_u64 v[80:81], v[156:157], 0, s[24:25]
	v_lshl_add_u64 v[116:117], v[80:81], 0, v[154:155]
	v_lshl_add_u64 v[118:119], v[124:125], 1, s[8:9]
	v_lshl_add_u64 v[82:83], v[116:117], 2, s[36:37]
	s_waitcnt vmcnt(1)
	v_pk_fma_f32 v[86:87], v[86:87], v[134:135], v[94:95]
	v_pk_fma_f32 v[84:85], v[84:85], v[132:133], v[92:93]
	s_waitcnt vmcnt(0)
	v_pk_fma_f32 v[92:93], v[108:109], v[130:131], v[102:103]
	v_pk_fma_f32 v[94:95], v[110:111], v[128:129], v[100:101]
	v_cvt_pk_bf16_f32 v84, v84, v85
	v_cvt_pk_bf16_f32 v85, v86, v87
	v_cvt_pk_bf16_f32 v86, v94, v95
	v_cvt_pk_bf16_f32 v87, v92, v93
	global_store_dwordx4 v[118:119], v[84:87], off nt
	global_load_dwordx4 v[84:87], v[82:83], off
	s_nop 0
	global_load_dwordx4 v[92:95], v[82:83], off offset:16
	v_pk_add_f32 v[100:101], v[74:75], 0 op_sel_hi:[1,0]
	v_pk_add_f32 v[102:103], v[72:73], 0 op_sel_hi:[1,0]
	v_lshl_add_u64 v[72:73], v[156:157], 0, s[38:39]
	v_lshl_add_u64 v[108:109], v[72:73], 0, v[154:155]
	v_lshl_add_u64 v[110:111], v[116:117], 1, s[8:9]
	v_lshl_add_u64 v[74:75], v[108:109], 2, s[36:37]
	s_waitcnt vmcnt(1)
	v_pk_fma_f32 v[78:79], v[78:79], v[134:135], v[86:87]
	v_pk_fma_f32 v[76:77], v[76:77], v[132:133], v[84:85]
	s_waitcnt vmcnt(0)
	v_pk_fma_f32 v[84:85], v[100:101], v[130:131], v[94:95]
	v_pk_fma_f32 v[86:87], v[102:103], v[128:129], v[92:93]
	v_cvt_pk_bf16_f32 v76, v76, v77
	v_cvt_pk_bf16_f32 v77, v78, v79
	v_cvt_pk_bf16_f32 v78, v86, v87
	v_cvt_pk_bf16_f32 v79, v84, v85
	global_store_dwordx4 v[110:111], v[76:79], off nt
	global_load_dwordx4 v[76:79], v[74:75], off
	s_nop 0
	global_load_dwordx4 v[84:87], v[74:75], off offset:16
	v_lshl_add_u64 v[92:93], v[108:109], 1, s[8:9]
	s_waitcnt vmcnt(1)
	v_pk_fma_f32 v[66:67], v[66:67], v[134:135], v[78:79]
	v_pk_fma_f32 v[64:65], v[64:65], v[132:133], v[76:77]
	s_waitcnt vmcnt(0)
	v_pk_fma_f32 v[76:77], v[58:59], v[130:131], v[86:87]
	v_pk_fma_f32 v[58:59], v[56:57], v[128:129], v[84:85]
	v_cvt_pk_bf16_f32 v56, v64, v65
	v_cvt_pk_bf16_f32 v57, v66, v67
	v_cvt_pk_bf16_f32 v58, v58, v59
	v_cvt_pk_bf16_f32 v59, v76, v77
	global_store_dwordx4 v[92:93], v[56:59], off nt
	global_load_dwordx4 v[76:79], v[160:161], off offset:512
	global_load_dwordx4 v[64:67], v[158:159], off offset:512
	s_nop 0
	global_load_dwordx4 v[56:59], v[158:159], off offset:528
	global_load_dwordx4 v[84:87], v[160:161], off offset:528
	v_pk_add_f32 v[92:93], v[60:61], 0 op_sel_hi:[1,0]
	v_or_b32_e32 v60, 0x80, v154
	v_ashrrev_i32_e32 v61, 31, v60
	v_lshl_add_u64 v[94:95], v[156:157], 0, v[60:61]
	v_lshl_add_u64 v[94:95], v[94:95], 1, s[8:9]
	s_waitcnt vmcnt(2)
; __device__ __forceinline__ unsigned pk2(float lo, float hi) { f32x2 v = {lo, hi}; bf16x2_t b = __builtin_convertvector(v, bf16x2_t); return __builtin_bit_cast(unsigned, b); }
;     __device__ __forceinline__ void operator()(const f32x4 (&acc)[2][2][4][2], const Unit& u, int wr, int wc, int fr, int fq) const {
;     ...
;         for (int bj = 0; bj < 2; ++bj) { const int c = col0 + bj * HALF;
;             const f32x4 g0 = *(const f32x4*)(gp + c), g1 = *(const f32x4*)(gp + c + 4);
;             const f32x4 b0 = bias ? *(const f32x4*)(bias + c) : (f32x4){0.f, 0.f, 0.f, 0.f}, b1 = bias ? *(const f32x4*)(bias + c + 4) : (f32x4){0.f, 0.f, 0.f, 0.f};
; #pragma unroll
;             for (int ai = 0; ai < 2; ++ai)
; #pragma unroll
;                 for (int m = 0; m < 4; ++m) { const size_t off = (size_t)(row0 + ai * HALF + m * 16) * 1024 + c;
;                     f32x4 x0, x1;
;                     if (BASE_BF16) { const u32x4 v = *(const u32x4*)((const bf16_t*)base + off);
;                         x0 = (f32x4){__uint_as_float(v.x << 16), __uint_as_float(v.x & 0xffff0000u), __uint_as_float(v.y << 16), __uint_as_float(v.y & 0xffff0000u)};
;                         x1 = (f32x4){__uint_as_float(v.z << 16), __uint_as_float(v.z & 0xffff0000u), __uint_as_float(v.w << 16), __uint_as_float(v.w & 0xffff0000u)}; }
;                     else { x0 = *(const f32x4*)((const float*)base + off); x1 = *(const f32x4*)((const float*)base + off + 4); }
;                     x0 = x0 + g0 * (acc[ai][bj][m][0] + b0); x1 = x1 + g1 * (acc[ai][bj][m][1] + b1);
;                     if (OUT_BF16) { u32x4 w; w.x = pk2(x0[0], x0[1]); w.y = pk2(x0[2], x0[3]); w.z = pk2(x1[0], x1[1]); w.w = pk2(x1[2], x1[3]); *(u32x4*)((bf16_t*)out + off) = w; }
;                     else { *(f32x4*)((float*)out + off) = x0; *(f32x4*)((float*)out + off + 4) = x1; } } }
	v_pk_fma_f32 v[70:71], v[70:71], v[66:67], v[78:79]
	v_pk_fma_f32 v[68:69], v[68:69], v[64:65], v[76:77]
	s_waitcnt vmcnt(0)
	v_pk_fma_f32 v[62:63], v[62:63], v[58:59], v[86:87]
	v_pk_fma_f32 v[76:77], v[92:93], v[56:57], v[84:85]
	v_cvt_pk_bf16_f32 v68, v68, v69
	v_cvt_pk_bf16_f32 v69, v70, v71
	v_cvt_pk_bf16_f32 v70, v76, v77
	v_cvt_pk_bf16_f32 v71, v62, v63
	global_store_dwordx4 v[94:95], v[68:71], off nt
	global_load_dwordx4 v[68:71], v[122:123], off offset:512
	s_nop 0
	global_load_dwordx4 v[76:79], v[122:123], off offset:528
	v_lshl_add_u64 v[62:63], v[120:121], 0, v[60:61]
	v_lshl_add_u64 v[62:63], v[62:63], 1, s[8:9]
	s_waitcnt vmcnt(1)
	v_pk_fma_f32 v[54:55], v[54:55], v[66:67], v[70:71]
	v_pk_fma_f32 v[52:53], v[52:53], v[64:65], v[68:69]
	s_waitcnt vmcnt(0)
	v_pk_fma_f32 v[68:69], v[50:51], v[58:59], v[78:79]
	v_pk_fma_f32 v[50:51], v[48:49], v[56:57], v[76:77]
	v_cvt_pk_bf16_f32 v48, v52, v53
	v_cvt_pk_bf16_f32 v49, v54, v55
	v_cvt_pk_bf16_f32 v50, v50, v51
	v_cvt_pk_bf16_f32 v51, v68, v69
	global_store_dwordx4 v[62:63], v[48:51], off nt
	global_load_dwordx4 v[48:51], v[114:115], off offset:512
	s_nop 0
	global_load_dwordx4 v[52:55], v[114:115], off offset:528
	v_lshl_add_u64 v[62:63], v[112:113], 0, v[60:61]
	v_lshl_add_u64 v[62:63], v[62:63], 1, s[8:9]
	s_waitcnt vmcnt(1)
	v_pk_fma_f32 v[46:47], v[46:47], v[66:67], v[50:51]
	v_pk_fma_f32 v[44:45], v[44:45], v[64:65], v[48:49]
	s_waitcnt vmcnt(0)
	v_pk_fma_f32 v[48:49], v[42:43], v[58:59], v[54:55]
	v_pk_fma_f32 v[42:43], v[40:41], v[56:57], v[52:53]
	v_cvt_pk_bf16_f32 v40, v44, v45
	v_cvt_pk_bf16_f32 v41, v46, v47
	v_cvt_pk_bf16_f32 v42, v42, v43
	v_cvt_pk_bf16_f32 v43, v48, v49
	global_store_dwordx4 v[62:63], v[40:43], off nt
	global_load_dwordx4 v[40:43], v[106:107], off offset:512
	s_nop 0
	global_load_dwordx4 v[44:47], v[106:107], off offset:528
	v_lshl_add_u64 v[48:49], v[104:105], 0, v[60:61]
	v_lshl_add_u64 v[48:49], v[48:49], 1, s[8:9]
	s_waitcnt vmcnt(1)
	v_pk_fma_f32 v[38:39], v[38:39], v[66:67], v[42:43]
	v_pk_fma_f32 v[36:37], v[36:37], v[64:65], v[40:41]
	s_waitcnt vmcnt(0)
	v_pk_fma_f32 v[40:41], v[34:35], v[58:59], v[46:47]
	v_pk_fma_f32 v[34:35], v[32:33], v[56:57], v[44:45]
	v_cvt_pk_bf16_f32 v32, v36, v37
	v_cvt_pk_bf16_f32 v33, v38, v39
	v_cvt_pk_bf16_f32 v34, v34, v35
	v_cvt_pk_bf16_f32 v35, v40, v41
	global_store_dwordx4 v[48:49], v[32:35], off nt
	global_load_dwordx4 v[32:35], v[98:99], off offset:512
	s_nop 0
	global_load_dwordx4 v[36:39], v[98:99], off offset:528
	v_lshl_add_u64 v[40:41], v[96:97], 0, v[60:61]
	v_lshl_add_u64 v[40:41], v[40:41], 1, s[8:9]
	s_waitcnt vmcnt(1)
	v_pk_fma_f32 v[30:31], v[30:31], v[66:67], v[34:35]
	v_pk_fma_f32 v[28:29], v[28:29], v[64:65], v[32:33]
	s_waitcnt vmcnt(0)
	v_pk_fma_f32 v[32:33], v[26:27], v[58:59], v[38:39]
	v_pk_fma_f32 v[26:27], v[24:25], v[56:57], v[36:37]
	v_cvt_pk_bf16_f32 v24, v28, v29
	v_cvt_pk_bf16_f32 v25, v30, v31
	v_cvt_pk_bf16_f32 v26, v26, v27
	v_cvt_pk_bf16_f32 v27, v32, v33
	global_store_dwordx4 v[40:41], v[24:27], off nt
	global_load_dwordx4 v[24:27], v[90:91], off offset:512
	s_nop 0
	global_load_dwordx4 v[28:31], v[90:91], off offset:528
	v_lshl_add_u64 v[32:33], v[88:89], 0, v[60:61]
	v_lshl_add_u64 v[32:33], v[32:33], 1, s[8:9]
	s_waitcnt vmcnt(1)
	v_pk_fma_f32 v[22:23], v[22:23], v[66:67], v[26:27]
	v_pk_fma_f32 v[20:21], v[20:21], v[64:65], v[24:25]
	s_waitcnt vmcnt(0)
	v_pk_fma_f32 v[24:25], v[18:19], v[58:59], v[30:31]
	v_pk_fma_f32 v[18:19], v[16:17], v[56:57], v[28:29]
	v_cvt_pk_bf16_f32 v16, v20, v21
	v_cvt_pk_bf16_f32 v17, v22, v23
	v_cvt_pk_bf16_f32 v18, v18, v19
	v_cvt_pk_bf16_f32 v19, v24, v25
	global_store_dwordx4 v[32:33], v[16:19], off nt
	global_load_dwordx4 v[16:19], v[82:83], off offset:512
	s_nop 0
	global_load_dwordx4 v[20:23], v[82:83], off offset:528
	v_lshl_add_u64 v[24:25], v[80:81], 0, v[60:61]
	v_lshl_add_u64 v[24:25], v[24:25], 1, s[8:9]
	s_waitcnt vmcnt(1)
	v_pk_fma_f32 v[14:15], v[14:15], v[66:67], v[18:19]
	v_pk_fma_f32 v[12:13], v[12:13], v[64:65], v[16:17]
	s_waitcnt vmcnt(0)
	v_pk_fma_f32 v[16:17], v[10:11], v[58:59], v[22:23]
	v_pk_fma_f32 v[10:11], v[8:9], v[56:57], v[20:21]
	v_cvt_pk_bf16_f32 v8, v12, v13
	v_cvt_pk_bf16_f32 v9, v14, v15
	v_cvt_pk_bf16_f32 v10, v10, v11
	v_cvt_pk_bf16_f32 v11, v16, v17
	global_store_dwordx4 v[24:25], v[8:11], off nt
	global_load_dwordx4 v[8:11], v[74:75], off offset:512
	s_nop 0
	global_load_dwordx4 v[12:15], v[74:75], off offset:528
	v_lshl_add_u64 v[16:17], v[72:73], 0, v[60:61]
	v_lshl_add_u64 v[16:17], v[16:17], 1, s[8:9]
	s_waitcnt vmcnt(1)
	v_pk_fma_f32 v[6:7], v[6:7], v[66:67], v[10:11]
	v_pk_fma_f32 v[4:5], v[4:5], v[64:65], v[8:9]
	s_waitcnt vmcnt(0)
	v_pk_fma_f32 v[8:9], v[2:3], v[58:59], v[14:15]
	v_pk_fma_f32 v[2:3], v[0:1], v[56:57], v[12:13]
	v_cvt_pk_bf16_f32 v0, v4, v5
	v_cvt_pk_bf16_f32 v1, v6, v7
	v_cvt_pk_bf16_f32 v2, v2, v3
	v_cvt_pk_bf16_f32 v3, v8, v9
	global_store_dwordx4 v[16:17], v[0:3], off nt
	s_cbranch_vccnz .LBB0_582
	s_andn2_b64 vcc, exec, s[6:7]
	s_cbranch_vccnz .LBB0_581
	s_barrier
	s_branch .LBB0_581

;     __device__ __forceinline__ void operator()(const f32x4 (&acc)[2][2][4][2], const Unit& u, int wr, int wc, int fr, int fq) const {
;         const int row0 = u.pm * BM + wr * 64 + fr; const int col0 = u.pn * BM + wc * 32 + 8 * fq;
;         const float* gp = gate + (size_t)(u.pm >> 5) * 6144;
; #pragma unroll
;         for (int bj = 0; bj < 2; ++bj) { const int c = col0 + bj * HALF;
;             const f32x4 g0 = *(const f32x4*)(gp + c), g1 = *(const f32x4*)(gp + c + 4);
;             const f32x4 b0 = bias ? *(const f32x4*)(bias + c) : (f32x4){0.f, 0.f, 0.f, 0.f}, b1 = bias ? *(const f32x4*)(bias + c + 4) : (f32x4){0.f, 0.f, 0.f, 0.f};
; #pragma unroll
;             for (int ai = 0; ai < 2; ++ai)
; #pragma unroll
;                 for (int m = 0; m < 4; ++m) { const size_t off = (size_t)(row0 + ai * HALF + m * 16) * 1024 + c;
;                     f32x4 x0, x1;
;                     if (BASE_BF16) { const u32x4 v = *(const u32x4*)((const bf16_t*)base + off);
;                         x0 = (f32x4){__uint_as_float(v.x << 16), __uint_as_float(v.x & 0xffff0000u), __uint_as_float(v.y << 16), __uint_as_float(v.y & 0xffff0000u)};
;                         x1 = (f32x4){__uint_as_float(v.z << 16), __uint_as_float(v.z & 0xffff0000u), __uint_as_float(v.w << 16), __uint_as_float(v.w & 0xffff0000u)}; }
;                     else { x0 = *(const f32x4*)((const float*)base + off); x1 = *(const f32x4*)((const float*)base + off + 4); }
;                     x0 = x0 + g0 * (acc[ai][bj][m][0] + b0); x1 = x1 + g1 * (acc[ai][bj][m][1] + b1);
.LBB0_792:
	v_lshl_add_u32 v148, s82, 8, v200
	v_lshl_or_b32 v128, s83, 8, v202
	s_ashr_i32 s33, s82, 5
	v_ashrrev_i32_e32 v149, 31, v148
	v_or_b32_e32 v140, 16, v148
	s_mul_hi_i32 s34, s33, 0x6000
	v_ashrrev_i32_e32 v129, 31, v128
	v_lshlrev_b64 v[130:131], 11, v[148:149]
	s_mulk_i32 s33, 0x6000
	v_ashrrev_i32_e32 v141, 31, v140
	v_lshl_add_u64 v[130:131], s[10:11], 0, v[130:131]
	v_lshlrev_b64 v[150:151], 1, v[128:129]
	s_add_u32 s42, s63, s33
	v_lshlrev_b64 v[140:141], 11, v[140:141]
	v_lshl_add_u64 v[170:171], v[130:131], 0, v[150:151]
	s_addc_u32 s43, s70, s34
	v_lshl_add_u64 v[140:141], s[10:11], 0, v[140:141]
	v_or_b32_e32 v144, 32, v148
	global_load_dwordx4 v[136:139], v[170:171], off
	v_lshl_add_u64 v[172:173], v[128:129], 2, s[42:43]
	v_lshl_add_u64 v[174:175], v[140:141], 0, v[150:151]
	v_ashrrev_i32_e32 v145, 31, v144
	global_load_dwordx4 v[128:131], v[172:173], off offset:16
	global_load_dwordx4 v[132:135], v[172:173], off
	global_load_dwordx4 v[140:143], v[174:175], off
	v_lshlrev_b64 v[144:145], 11, v[144:145]
	v_pk_add_f32 v[188:189], v[122:123], 0 op_sel_hi:[1,0]
	v_or_b32_e32 v122, 48, v148
	v_lshl_add_u64 v[144:145], s[10:11], 0, v[144:145]
	v_ashrrev_i32_e32 v123, 31, v122
	v_lshl_add_u64 v[176:177], v[144:145], 0, v[150:151]
	v_lshlrev_b64 v[122:123], 11, v[122:123]
	global_load_dwordx4 v[144:147], v[176:177], off
	v_lshl_add_u64 v[122:123], s[10:11], 0, v[122:123]
	v_lshl_add_u64 v[178:179], v[122:123], 0, v[150:151]
	v_pk_add_f32 v[184:185], v[126:127], 0 op_sel_hi:[1,0]
	v_pk_add_f32 v[186:187], v[124:125], 0 op_sel_hi:[1,0]
	global_load_dwordx4 v[124:127], v[178:179], off
	v_pk_add_f32 v[198:199], v[120:121], 0 op_sel_hi:[1,0]
	v_add_co_u32_e32 v182, vcc, s76, v170
	v_pk_add_f32 v[190:191], v[118:119], 0 op_sel_hi:[1,0]
	v_pk_add_f32 v[192:193], v[116:117], 0 op_sel_hi:[1,0]
	v_pk_add_f32 v[194:195], v[114:115], 0 op_sel_hi:[1,0]
	v_pk_add_f32 v[196:197], v[112:113], 0 op_sel_hi:[1,0]
	v_addc_co_u32_e32 v183, vcc, 0, v171, vcc
	v_add_co_u32_e32 v180, vcc, s77, v170
	v_pk_add_f32 v[108:109], v[108:109], 0 op_sel_hi:[1,0]
	s_nop 0
	v_addc_co_u32_e32 v181, vcc, 0, v171, vcc
	global_load_dwordx4 v[112:115], v[170:171], off offset:256
	global_load_dwordx4 v[206:209], v[182:183], off
	global_load_dwordx4 v[148:151], v[180:181], off
	global_load_dwordx4 v[116:119], v[174:175], off offset:256
	global_load_dwordx4 v[120:123], v[176:177], off offset:256
	v_pk_add_f32 v[106:107], v[106:107], 0 op_sel_hi:[1,0]
	v_pk_add_f32 v[104:105], v[104:105], 0 op_sel_hi:[1,0]
	v_pk_add_f32 v[110:111], v[110:111], 0 op_sel_hi:[1,0]
	v_pk_add_f32 v[100:101], v[100:101], 0 op_sel_hi:[1,0]
	v_pk_add_f32 v[102:103], v[102:103], 0 op_sel_hi:[1,0]
	v_pk_add_f32 v[98:99], v[98:99], 0 op_sel_hi:[1,0]
	v_pk_add_f32 v[96:97], v[96:97], 0 op_sel_hi:[1,0]
	v_pk_add_f32 v[94:95], v[94:95], 0 op_sel_hi:[1,0]
	v_pk_add_f32 v[92:93], v[92:93], 0 op_sel_hi:[1,0]
	v_pk_add_f32 v[90:91], v[90:91], 0 op_sel_hi:[1,0]
	v_pk_add_f32 v[88:89], v[88:89], 0 op_sel_hi:[1,0]
	v_pk_add_f32 v[86:87], v[86:87], 0 op_sel_hi:[1,0]
	v_pk_add_f32 v[84:85], v[84:85], 0 op_sel_hi:[1,0]
	v_pk_add_f32 v[82:83], v[82:83], 0 op_sel_hi:[1,0]
	v_pk_add_f32 v[80:81], v[80:81], 0 op_sel_hi:[1,0]
	v_pk_add_f32 v[78:79], v[78:79], 0 op_sel_hi:[1,0]
	v_pk_add_f32 v[76:77], v[76:77], 0 op_sel_hi:[1,0]
	v_pk_add_f32 v[74:75], v[74:75], 0 op_sel_hi:[1,0]
	v_pk_add_f32 v[72:73], v[72:73], 0 op_sel_hi:[1,0]
	v_pk_add_f32 v[58:59], v[58:59], 0 op_sel_hi:[1,0]
	v_pk_add_f32 v[56:57], v[56:57], 0 op_sel_hi:[1,0]
	v_pk_add_f32 v[50:51], v[50:51], 0 op_sel_hi:[1,0]
	v_pk_add_f32 v[48:49], v[48:49], 0 op_sel_hi:[1,0]
	v_pk_add_f32 v[70:71], v[70:71], 0 op_sel_hi:[1,0]
	v_pk_add_f32 v[68:69], v[68:69], 0 op_sel_hi:[1,0]
	v_pk_add_f32 v[66:67], v[66:67], 0 op_sel_hi:[1,0]
	v_pk_add_f32 v[64:65], v[64:65], 0 op_sel_hi:[1,0]
	v_pk_add_f32 v[62:63], v[62:63], 0 op_sel_hi:[1,0]
	v_pk_add_f32 v[60:61], v[60:61], 0 op_sel_hi:[1,0]
	v_pk_add_f32 v[54:55], v[54:55], 0 op_sel_hi:[1,0]
	v_pk_add_f32 v[52:53], v[52:53], 0 op_sel_hi:[1,0]
	v_pk_add_f32 v[46:47], v[46:47], 0 op_sel_hi:[1,0]
	v_pk_add_f32 v[44:45], v[44:45], 0 op_sel_hi:[1,0]
	v_pk_add_f32 v[42:43], v[42:43], 0 op_sel_hi:[1,0]
	v_pk_add_f32 v[40:41], v[40:41], 0 op_sel_hi:[1,0]
	v_pk_add_f32 v[38:39], v[38:39], 0 op_sel_hi:[1,0]
	v_pk_add_f32 v[36:37], v[36:37], 0 op_sel_hi:[1,0]
	v_pk_add_f32 v[34:35], v[34:35], 0 op_sel_hi:[1,0]
	v_pk_add_f32 v[32:33], v[32:33], 0 op_sel_hi:[1,0]
	v_pk_add_f32 v[30:31], v[30:31], 0 op_sel_hi:[1,0]
	v_pk_add_f32 v[28:29], v[28:29], 0 op_sel_hi:[1,0]
	v_pk_add_f32 v[26:27], v[26:27], 0 op_sel_hi:[1,0]
	v_pk_add_f32 v[24:25], v[24:25], 0 op_sel_hi:[1,0]
	v_pk_add_f32 v[22:23], v[22:23], 0 op_sel_hi:[1,0]
	v_pk_add_f32 v[20:21], v[20:21], 0 op_sel_hi:[1,0]
	v_pk_add_f32 v[18:19], v[18:19], 0 op_sel_hi:[1,0]
	s_waitcnt vmcnt(0)
; __device__ __forceinline__ unsigned pk2(float lo, float hi) { f32x2 v = {lo, hi}; bf16x2_t b = __builtin_convertvector(v, bf16x2_t); return __builtin_bit_cast(unsigned, b); }
;     __device__ __forceinline__ void operator()(const f32x4 (&acc)[2][2][4][2], const Unit& u, int wr, int wc, int fr, int fq) const {
;     ...
;                 for (int m = 0; m < 4; ++m) { const size_t off = (size_t)(row0 + ai * HALF + m * 16) * 1024 + c;
;                     f32x4 x0, x1;
;                     if (BASE_BF16) { const u32x4 v = *(const u32x4*)((const bf16_t*)base + off);
;                         x0 = (f32x4){__uint_as_float(v.x << 16), __uint_as_float(v.x & 0xffff0000u), __uint_as_float(v.y << 16), __uint_as_float(v.y & 0xffff0000u)};
;                         x1 = (f32x4){__uint_as_float(v.z << 16), __uint_as_float(v.z & 0xffff0000u), __uint_as_float(v.w << 16), __uint_as_float(v.w & 0xffff0000u)}; }
;                     else { x0 = *(const f32x4*)((const float*)base + off); x1 = *(const f32x4*)((const float*)base + off + 4); }
;                     x0 = x0 + g0 * (acc[ai][bj][m][0] + b0); x1 = x1 + g1 * (acc[ai][bj][m][1] + b1);
;                     if (OUT_BF16) { u32x4 w; w.x = pk2(x0[0], x0[1]); w.y = pk2(x0[2], x0[3]); w.z = pk2(x1[0], x1[1]); w.w = pk2(x1[2], x1[3]); *(u32x4*)((bf16_t*)out + off) = w; }
;                     else { *(f32x4*)((float*)out + off) = x0; *(f32x4*)((float*)out + off + 4) = x1; } } }
	v_lshlrev_b32_e32 v210, 16, v136
	v_and_b32_e32 v211, 0xffff0000, v136
	v_lshlrev_b32_e32 v136, 16, v137
	v_and_b32_e32 v137, 0xffff0000, v137
	v_lshlrev_b32_e32 v212, 16, v138
	v_and_b32_e32 v213, 0xffff0000, v138
	v_lshlrev_b32_e32 v138, 16, v139
	v_and_b32_e32 v139, 0xffff0000, v139
	v_pk_fma_f32 v[184:185], v[184:185], v[134:135], v[136:137]
	v_pk_fma_f32 v[136:137], v[186:187], v[132:133], v[210:211]
	v_pk_fma_f32 v[186:187], v[188:189], v[130:131], v[138:139]
	v_pk_fma_f32 v[138:139], v[198:199], v[128:129], v[212:213]
	v_lshlrev_b32_e32 v188, 16, v140
	v_and_b32_e32 v189, 0xffff0000, v140
	v_lshlrev_b32_e32 v140, 16, v141
	v_and_b32_e32 v141, 0xffff0000, v141
	v_lshlrev_b32_e32 v198, 16, v142
	v_and_b32_e32 v199, 0xffff0000, v142
	v_lshlrev_b32_e32 v142, 16, v143
	v_and_b32_e32 v143, 0xffff0000, v143
	v_cvt_pk_bf16_f32 v136, v136, v137
	v_cvt_pk_bf16_f32 v137, v184, v185
	v_cvt_pk_bf16_f32 v138, v138, v139
	v_cvt_pk_bf16_f32 v139, v186, v187
	v_pk_fma_f32 v[140:141], v[190:191], v[134:135], v[140:141]
	v_pk_fma_f32 v[184:185], v[192:193], v[132:133], v[188:189]
	v_pk_fma_f32 v[142:143], v[194:195], v[130:131], v[142:143]
	v_pk_fma_f32 v[186:187], v[196:197], v[128:129], v[198:199]
	global_store_dwordx4 v[170:171], v[136:139], off nt
	v_pk_add_f32 v[16:17], v[16:17], 0 op_sel_hi:[1,0]
	v_pk_add_f32 v[14:15], v[14:15], 0 op_sel_hi:[1,0]
	v_cvt_pk_bf16_f32 v136, v184, v185
	v_cvt_pk_bf16_f32 v137, v140, v141
	v_cvt_pk_bf16_f32 v138, v186, v187
	v_cvt_pk_bf16_f32 v139, v142, v143
	global_store_dwordx4 v[174:175], v[136:139], off nt
	v_lshlrev_b32_e32 v140, 16, v146
	v_and_b32_e32 v141, 0xffff0000, v146
	v_lshlrev_b32_e32 v136, 16, v144
	v_and_b32_e32 v137, 0xffff0000, v144
	v_lshlrev_b32_e32 v142, 16, v147
	v_and_b32_e32 v143, 0xffff0000, v147
	v_pk_fma_f32 v[108:109], v[108:109], v[132:133], v[136:137]
	v_pk_fma_f32 v[136:137], v[106:107], v[130:131], v[142:143]
	v_pk_fma_f32 v[106:107], v[104:105], v[128:129], v[140:141]
	v_add_co_u32_e32 v140, vcc, s78, v170
	v_lshlrev_b32_e32 v138, 16, v145
	v_and_b32_e32 v139, 0xffff0000, v145
	v_addc_co_u32_e32 v141, vcc, 0, v171, vcc
	v_cvt_pk_bf16_f32 v106, v106, v107
	v_cvt_pk_bf16_f32 v107, v136, v137
	v_lshlrev_b32_e32 v136, 16, v124
	v_and_b32_e32 v137, 0xffff0000, v124
	v_pk_fma_f32 v[138:139], v[110:111], v[134:135], v[138:139]
	v_cvt_pk_bf16_f32 v104, v108, v109
	global_load_dwordx4 v[108:111], v[140:141], off
	v_pk_fma_f32 v[100:101], v[100:101], v[132:133], v[136:137]
	v_add_co_u32_e32 v136, vcc, s79, v170
	v_lshlrev_b32_e32 v124, 16, v125
	v_and_b32_e32 v125, 0xffff0000, v125
	v_addc_co_u32_e32 v137, vcc, 0, v171, vcc
	v_cvt_pk_bf16_f32 v105, v138, v139
	v_lshlrev_b32_e32 v138, 16, v126
	v_and_b32_e32 v139, 0xffff0000, v126
	v_lshlrev_b32_e32 v142, 16, v127
	v_and_b32_e32 v143, 0xffff0000, v127
	v_pk_fma_f32 v[102:103], v[102:103], v[134:135], v[124:125]
	global_load_dwordx4 v[124:127], v[136:137], off
	v_pk_fma_f32 v[142:143], v[98:99], v[130:131], v[142:143]
	v_pk_fma_f32 v[98:99], v[96:97], v[128:129], v[138:139]
	v_cvt_pk_bf16_f32 v97, v102, v103
	v_cvt_pk_bf16_f32 v98, v98, v99
	v_cvt_pk_bf16_f32 v99, v142, v143
	v_lshlrev_b32_e32 v102, 16, v206
	v_and_b32_e32 v103, 0xffff0000, v206
	v_lshlrev_b32_e32 v138, 16, v207
	v_and_b32_e32 v139, 0xffff0000, v207
	v_lshlrev_b32_e32 v142, 16, v208
	v_and_b32_e32 v143, 0xffff0000, v208
	v_lshlrev_b32_e32 v144, 16, v209
	v_and_b32_e32 v145, 0xffff0000, v209
	v_pk_fma_f32 v[94:95], v[94:95], v[134:135], v[138:139]
	v_pk_fma_f32 v[92:93], v[92:93], v[132:133], v[102:103]
	v_pk_fma_f32 v[102:103], v[90:91], v[130:131], v[144:145]
	v_pk_fma_f32 v[90:91], v[88:89], v[128:129], v[142:143]
	v_cvt_pk_bf16_f32 v89, v94, v95
	v_cvt_pk_bf16_f32 v90, v90, v91
	v_cvt_pk_bf16_f32 v91, v102, v103
	v_lshlrev_b32_e32 v94, 16, v148
	v_and_b32_e32 v95, 0xffff0000, v148
	v_lshlrev_b32_e32 v102, 16, v149
	v_and_b32_e32 v103, 0xffff0000, v149
	v_lshlrev_b32_e32 v138, 16, v150
	v_and_b32_e32 v139, 0xffff0000, v150
	v_lshlrev_b32_e32 v142, 16, v151
	v_and_b32_e32 v143, 0xffff0000, v151
	v_pk_fma_f32 v[86:87], v[86:87], v[134:135], v[102:103]
	v_pk_fma_f32 v[84:85], v[84:85], v[132:133], v[94:95]
	v_pk_fma_f32 v[94:95], v[82:83], v[130:131], v[142:143]
	v_pk_fma_f32 v[82:83], v[80:81], v[128:129], v[138:139]
	v_cvt_pk_bf16_f32 v81, v86, v87
	v_cvt_pk_bf16_f32 v82, v82, v83
	v_cvt_pk_bf16_f32 v83, v94, v95
	v_cvt_pk_bf16_f32 v96, v100, v101
	v_cvt_pk_bf16_f32 v88, v92, v93
	v_cvt_pk_bf16_f32 v80, v84, v85
	global_store_dwordx4 v[176:177], v[104:107], off nt
	global_store_dwordx4 v[178:179], v[96:99], off nt
	v_lshl_add_u64 v[100:101], v[170:171], 0, s[22:23]
	global_store_dwordx4 v[182:183], v[88:91], off nt
	v_lshl_add_u64 v[92:93], v[170:171], 0, s[24:25]
	global_store_dwordx4 v[180:181], v[80:83], off nt
	global_load_dwordx4 v[104:107], v[178:179], off offset:256
	global_load_dwordx4 v[96:99], v[100:101], off offset:256
	v_lshl_add_u64 v[80:81], v[170:171], 0, s[36:37]
	global_load_dwordx4 v[88:91], v[92:93], off offset:256
	global_load_dwordx4 v[82:85], v[80:81], off offset:256
	v_pk_add_f32 v[12:13], v[12:13], 0 op_sel_hi:[1,0]
	v_pk_add_f32 v[10:11], v[10:11], 0 op_sel_hi:[1,0]
	v_pk_add_f32 v[8:9], v[8:9], 0 op_sel_hi:[1,0]
	v_pk_add_f32 v[6:7], v[6:7], 0 op_sel_hi:[1,0]
	v_pk_add_f32 v[4:5], v[4:5], 0 op_sel_hi:[1,0]
	v_pk_add_f32 v[2:3], v[2:3], 0 op_sel_hi:[1,0]
	v_pk_add_f32 v[0:1], v[0:1], 0 op_sel_hi:[1,0]
	s_and_b64 vcc, exec, s[0:1]
	s_mov_b64 s[0:1], -1
	s_waitcnt vmcnt(9)
; __device__ __forceinline__ unsigned pk2(float lo, float hi) { f32x2 v = {lo, hi}; bf16x2_t b = __builtin_convertvector(v, bf16x2_t); return __builtin_bit_cast(unsigned, b); }
;     __device__ __forceinline__ void operator()(const f32x4 (&acc)[2][2][4][2], const Unit& u, int wr, int wc, int fr, int fq) const {
;     ...
;                 for (int m = 0; m < 4; ++m) { const size_t off = (size_t)(row0 + ai * HALF + m * 16) * 1024 + c;
;                     f32x4 x0, x1;
;                     if (BASE_BF16) { const u32x4 v = *(const u32x4*)((const bf16_t*)base + off);
;                         x0 = (f32x4){__uint_as_float(v.x << 16), __uint_as_float(v.x & 0xffff0000u), __uint_as_float(v.y << 16), __uint_as_float(v.y & 0xffff0000u)};
;                         x1 = (f32x4){__uint_as_float(v.z << 16), __uint_as_float(v.z & 0xffff0000u), __uint_as_float(v.w << 16), __uint_as_float(v.w & 0xffff0000u)}; }
;                     else { x0 = *(const f32x4*)((const float*)base + off); x1 = *(const f32x4*)((const float*)base + off + 4); }
;                     x0 = x0 + g0 * (acc[ai][bj][m][0] + b0); x1 = x1 + g1 * (acc[ai][bj][m][1] + b1);
;                     if (OUT_BF16) { u32x4 w; w.x = pk2(x0[0], x0[1]); w.y = pk2(x0[2], x0[3]); w.z = pk2(x1[0], x1[1]); w.w = pk2(x1[2], x1[3]); *(u32x4*)((bf16_t*)out + off) = w; }
;                     else { *(f32x4*)((float*)out + off) = x0; *(f32x4*)((float*)out + off + 4) = x1; } } }
	v_lshlrev_b32_e32 v86, 16, v108
	v_and_b32_e32 v87, 0xffff0000, v108
	v_lshlrev_b32_e32 v94, 16, v109
	v_and_b32_e32 v95, 0xffff0000, v109
	v_lshlrev_b32_e32 v102, 16, v110
	v_and_b32_e32 v103, 0xffff0000, v110
	v_lshlrev_b32_e32 v108, 16, v111
	v_and_b32_e32 v109, 0xffff0000, v111
	v_pk_fma_f32 v[78:79], v[78:79], v[134:135], v[94:95]
	v_pk_fma_f32 v[76:77], v[76:77], v[132:133], v[86:87]
	v_pk_fma_f32 v[86:87], v[74:75], v[130:131], v[108:109]
	v_pk_fma_f32 v[74:75], v[72:73], v[128:129], v[102:103]
	v_cvt_pk_bf16_f32 v73, v78, v79
	v_cvt_pk_bf16_f32 v74, v74, v75
	v_cvt_pk_bf16_f32 v75, v86, v87
	s_waitcnt vmcnt(8)
	v_lshlrev_b32_e32 v78, 16, v124
	v_and_b32_e32 v79, 0xffff0000, v124
	v_lshlrev_b32_e32 v86, 16, v125
	v_and_b32_e32 v87, 0xffff0000, v125
	v_lshlrev_b32_e32 v94, 16, v126
	v_and_b32_e32 v95, 0xffff0000, v126
	v_lshlrev_b32_e32 v102, 16, v127
	v_and_b32_e32 v103, 0xffff0000, v127
	v_pk_fma_f32 v[58:59], v[58:59], v[134:135], v[86:87]
	v_pk_fma_f32 v[56:57], v[56:57], v[132:133], v[78:79]
	v_pk_fma_f32 v[78:79], v[50:51], v[130:131], v[102:103]
	v_pk_fma_f32 v[50:51], v[48:49], v[128:129], v[94:95]
	v_cvt_pk_bf16_f32 v72, v76, v77
	v_cvt_pk_bf16_f32 v48, v56, v57
	v_cvt_pk_bf16_f32 v49, v58, v59
	v_cvt_pk_bf16_f32 v50, v50, v51
	v_cvt_pk_bf16_f32 v51, v78, v79
	global_store_dwordx4 v[140:141], v[72:75], off nt
	v_lshl_add_u64 v[76:77], v[170:171], 0, s[38:39]
	global_store_dwordx4 v[136:137], v[48:51], off nt
	global_load_dwordx4 v[72:75], v[76:77], off offset:256
	s_nop 0
	global_load_dwordx4 v[48:51], v[172:173], off offset:512
	global_load_dwordx4 v[56:59], v[172:173], off offset:528
	v_lshlrev_b32_e32 v78, 16, v112
	v_and_b32_e32 v79, 0xffff0000, v112
	v_lshlrev_b32_e32 v86, 16, v113
	v_and_b32_e32 v87, 0xffff0000, v113
	v_lshlrev_b32_e32 v94, 16, v114
	v_and_b32_e32 v95, 0xffff0000, v114
	v_lshlrev_b32_e32 v102, 16, v115
	v_and_b32_e32 v103, 0xffff0000, v115
	s_waitcnt vmcnt(1)
	v_pk_fma_f32 v[70:71], v[70:71], v[50:51], v[86:87]
	v_pk_fma_f32 v[68:69], v[68:69], v[48:49], v[78:79]
	s_waitcnt vmcnt(0)
; __device__ __forceinline__ unsigned pk2(float lo, float hi) { f32x2 v = {lo, hi}; bf16x2_t b = __builtin_convertvector(v, bf16x2_t); return __builtin_bit_cast(unsigned, b); }
;     __device__ __forceinline__ void operator()(const f32x4 (&acc)[2][2][4][2], const Unit& u, int wr, int wc, int fr, int fq) const {
;     ...
;         for (int bj = 0; bj < 2; ++bj) { const int c = col0 + bj * HALF;
;             const f32x4 g0 = *(const f32x4*)(gp + c), g1 = *(const f32x4*)(gp + c + 4);
;             const f32x4 b0 = bias ? *(const f32x4*)(bias + c) : (f32x4){0.f, 0.f, 0.f, 0.f}, b1 = bias ? *(const f32x4*)(bias + c + 4) : (f32x4){0.f, 0.f, 0.f, 0.f};
; #pragma unroll
;             for (int ai = 0; ai < 2; ++ai)
; #pragma unroll
;                 for (int m = 0; m < 4; ++m) { const size_t off = (size_t)(row0 + ai * HALF + m * 16) * 1024 + c;
;                     f32x4 x0, x1;
;                     if (BASE_BF16) { const u32x4 v = *(const u32x4*)((const bf16_t*)base + off);
;                         x0 = (f32x4){__uint_as_float(v.x << 16), __uint_as_float(v.x & 0xffff0000u), __uint_as_float(v.y << 16), __uint_as_float(v.y & 0xffff0000u)};
;                         x1 = (f32x4){__uint_as_float(v.z << 16), __uint_as_float(v.z & 0xffff0000u), __uint_as_float(v.w << 16), __uint_as_float(v.w & 0xffff0000u)}; }
;                     else { x0 = *(const f32x4*)((const float*)base + off); x1 = *(const f32x4*)((const float*)base + off + 4); }
;                     x0 = x0 + g0 * (acc[ai][bj][m][0] + b0); x1 = x1 + g1 * (acc[ai][bj][m][1] + b1);
;                     if (OUT_BF16) { u32x4 w; w.x = pk2(x0[0], x0[1]); w.y = pk2(x0[2], x0[3]); w.z = pk2(x1[0], x1[1]); w.w = pk2(x1[2], x1[3]); *(u32x4*)((bf16_t*)out + off) = w; }
;                     else { *(f32x4*)((float*)out + off) = x0; *(f32x4*)((float*)out + off + 4) = x1; } } }
	v_pk_fma_f32 v[78:79], v[66:67], v[58:59], v[102:103]
	v_pk_fma_f32 v[66:67], v[64:65], v[56:57], v[94:95]
	v_cvt_pk_bf16_f32 v64, v68, v69
	v_cvt_pk_bf16_f32 v65, v70, v71
	v_cvt_pk_bf16_f32 v66, v66, v67
	v_cvt_pk_bf16_f32 v67, v78, v79
	global_store_dwordx4 v[170:171], v[64:67], off offset:256 nt
	v_lshlrev_b32_e32 v68, 16, v118
	v_and_b32_e32 v69, 0xffff0000, v118
	v_lshlrev_b32_e32 v64, 16, v116
	v_and_b32_e32 v65, 0xffff0000, v116
	v_lshlrev_b32_e32 v66, 16, v117
	v_and_b32_e32 v67, 0xffff0000, v117
	v_lshlrev_b32_e32 v70, 16, v119
	v_and_b32_e32 v71, 0xffff0000, v119
	v_pk_fma_f32 v[62:63], v[62:63], v[50:51], v[66:67]
	v_pk_fma_f32 v[60:61], v[60:61], v[48:49], v[64:65]
	v_pk_fma_f32 v[64:65], v[54:55], v[58:59], v[70:71]
	v_pk_fma_f32 v[54:55], v[52:53], v[56:57], v[68:69]
	v_cvt_pk_bf16_f32 v52, v60, v61
	v_cvt_pk_bf16_f32 v53, v62, v63
	v_cvt_pk_bf16_f32 v54, v54, v55
	v_cvt_pk_bf16_f32 v55, v64, v65
	global_store_dwordx4 v[174:175], v[52:55], off offset:256 nt
	v_lshlrev_b32_e32 v60, 16, v122
	v_and_b32_e32 v61, 0xffff0000, v122
	v_lshlrev_b32_e32 v52, 16, v120
	v_and_b32_e32 v53, 0xffff0000, v120
	v_lshlrev_b32_e32 v54, 16, v121
	v_and_b32_e32 v55, 0xffff0000, v121
	v_lshlrev_b32_e32 v62, 16, v123
	v_and_b32_e32 v63, 0xffff0000, v123
	v_pk_fma_f32 v[46:47], v[46:47], v[50:51], v[54:55]
	v_pk_fma_f32 v[44:45], v[44:45], v[48:49], v[52:53]
	v_pk_fma_f32 v[52:53], v[42:43], v[58:59], v[62:63]
	v_pk_fma_f32 v[42:43], v[40:41], v[56:57], v[60:61]
	v_cvt_pk_bf16_f32 v40, v44, v45
	v_cvt_pk_bf16_f32 v41, v46, v47
	v_cvt_pk_bf16_f32 v42, v42, v43
	v_cvt_pk_bf16_f32 v43, v52, v53
	global_store_dwordx4 v[176:177], v[40:43], off offset:256 nt
	v_lshlrev_b32_e32 v44, 16, v106
	v_and_b32_e32 v45, 0xffff0000, v106
	v_lshlrev_b32_e32 v40, 16, v104
	v_and_b32_e32 v41, 0xffff0000, v104
	v_lshlrev_b32_e32 v42, 16, v105
	v_and_b32_e32 v43, 0xffff0000, v105
	v_lshlrev_b32_e32 v46, 16, v107
	v_and_b32_e32 v47, 0xffff0000, v107
	v_pk_fma_f32 v[38:39], v[38:39], v[50:51], v[42:43]
	v_pk_fma_f32 v[36:37], v[36:37], v[48:49], v[40:41]
	v_pk_fma_f32 v[40:41], v[34:35], v[58:59], v[46:47]
	v_pk_fma_f32 v[34:35], v[32:33], v[56:57], v[44:45]
	v_cvt_pk_bf16_f32 v32, v36, v37
	v_cvt_pk_bf16_f32 v33, v38, v39
	v_cvt_pk_bf16_f32 v34, v34, v35
	v_cvt_pk_bf16_f32 v35, v40, v41
	global_store_dwordx4 v[178:179], v[32:35], off offset:256 nt
	v_lshlrev_b32_e32 v36, 16, v98
	v_and_b32_e32 v37, 0xffff0000, v98
	v_lshlrev_b32_e32 v32, 16, v96
	v_and_b32_e32 v33, 0xffff0000, v96
	v_lshlrev_b32_e32 v34, 16, v97
	v_and_b32_e32 v35, 0xffff0000, v97
	v_lshlrev_b32_e32 v38, 16, v99
	v_and_b32_e32 v39, 0xffff0000, v99
	v_pk_fma_f32 v[30:31], v[30:31], v[50:51], v[34:35]
	v_pk_fma_f32 v[28:29], v[28:29], v[48:49], v[32:33]
	v_pk_fma_f32 v[32:33], v[26:27], v[58:59], v[38:39]
	v_pk_fma_f32 v[26:27], v[24:25], v[56:57], v[36:37]
	v_cvt_pk_bf16_f32 v24, v28, v29
	v_cvt_pk_bf16_f32 v25, v30, v31
	v_cvt_pk_bf16_f32 v26, v26, v27
	v_cvt_pk_bf16_f32 v27, v32, v33
	global_store_dwordx4 v[100:101], v[24:27], off offset:256 nt
	v_lshlrev_b32_e32 v28, 16, v90
	v_and_b32_e32 v29, 0xffff0000, v90
	v_lshlrev_b32_e32 v24, 16, v88
	v_and_b32_e32 v25, 0xffff0000, v88
	v_lshlrev_b32_e32 v26, 16, v89
	v_and_b32_e32 v27, 0xffff0000, v89
	v_lshlrev_b32_e32 v30, 16, v91
	v_and_b32_e32 v31, 0xffff0000, v91
	v_pk_fma_f32 v[22:23], v[22:23], v[50:51], v[26:27]
	v_pk_fma_f32 v[20:21], v[20:21], v[48:49], v[24:25]
	v_pk_fma_f32 v[24:25], v[18:19], v[58:59], v[30:31]
	v_pk_fma_f32 v[18:19], v[16:17], v[56:57], v[28:29]
	v_cvt_pk_bf16_f32 v16, v20, v21
	v_cvt_pk_bf16_f32 v17, v22, v23
	v_cvt_pk_bf16_f32 v18, v18, v19
	v_cvt_pk_bf16_f32 v19, v24, v25
	global_store_dwordx4 v[92:93], v[16:19], off offset:256 nt
	v_lshlrev_b32_e32 v20, 16, v84
	v_and_b32_e32 v21, 0xffff0000, v84
	v_lshlrev_b32_e32 v16, 16, v82
	v_and_b32_e32 v17, 0xffff0000, v82
	v_lshlrev_b32_e32 v18, 16, v83
	v_and_b32_e32 v19, 0xffff0000, v83
	v_lshlrev_b32_e32 v22, 16, v85
	v_and_b32_e32 v23, 0xffff0000, v85
	v_pk_fma_f32 v[14:15], v[14:15], v[50:51], v[18:19]
	v_pk_fma_f32 v[12:13], v[12:13], v[48:49], v[16:17]
	v_pk_fma_f32 v[16:17], v[10:11], v[58:59], v[22:23]
	v_pk_fma_f32 v[10:11], v[8:9], v[56:57], v[20:21]
	v_cvt_pk_bf16_f32 v8, v12, v13
	v_cvt_pk_bf16_f32 v9, v14, v15
	v_cvt_pk_bf16_f32 v10, v10, v11
	v_cvt_pk_bf16_f32 v11, v16, v17
	global_store_dwordx4 v[80:81], v[8:11], off offset:256 nt
	v_lshlrev_b32_e32 v12, 16, v74
	v_and_b32_e32 v13, 0xffff0000, v74
	v_lshlrev_b32_e32 v8, 16, v72
	v_and_b32_e32 v9, 0xffff0000, v72
	v_lshlrev_b32_e32 v10, 16, v73
	v_and_b32_e32 v11, 0xffff0000, v73
	v_lshlrev_b32_e32 v14, 16, v75
	v_and_b32_e32 v15, 0xffff0000, v75
	v_pk_fma_f32 v[6:7], v[6:7], v[50:51], v[10:11]
	v_pk_fma_f32 v[4:5], v[4:5], v[48:49], v[8:9]
	v_pk_fma_f32 v[8:9], v[2:3], v[58:59], v[14:15]
	v_pk_fma_f32 v[2:3], v[0:1], v[56:57], v[12:13]
	v_cvt_pk_bf16_f32 v0, v4, v5
	v_cvt_pk_bf16_f32 v1, v6, v7
	v_cvt_pk_bf16_f32 v2, v2, v3
	v_cvt_pk_bf16_f32 v3, v8, v9
	global_store_dwordx4 v[76:77], v[0:3], off offset:256 nt
	s_cbranch_vccnz .LBB0_777
	s_andn2_b64 vcc, exec, s[8:9]
	s_cbranch_vccnz .LBB0_776
	s_barrier
	s_branch .LBB0_776

; __device__ __forceinline__ unsigned pk2(float lo, float hi) { f32x2 v = {lo, hi}; bf16x2_t b = __builtin_convertvector(v, bf16x2_t); return __builtin_bit_cast(unsigned, b); }
;     __device__ __forceinline__ void operator()(const f32x4 (&acc)[2][2][4][2], const Unit& u, int wr, int wc, int fr, int fq) const {
;         const int row0 = u.pm * BM + wr * 64 + fr; const int col0 = u.pn * BM + wc * 32 + 8 * fq;
; #pragma unroll
;         for (int ai = 0; ai < 2; ++ai)
; #pragma unroll
;             for (int m = 0; m < 4; ++m) { const int row = row0 + ai * HALF + m * 16; const float rb = rowbias ? rowbias[row] : 0.f; bf16_t* rowp = O + (size_t)row * ldc + col0;
; #pragma unroll
;                 for (int bj = 0; bj < 2; ++bj) { const f32x4 v0 = acc[ai][bj][m][0] + rb, v1 = acc[ai][bj][m][1] + rb;
;                     u32x4 w; w.x = pk2(v0[0], v0[1]); w.y = pk2(v0[2], v0[3]); w.z = pk2(v1[0], v1[1]); w.w = pk2(v1[2], v1[3]);
;                     *(u32x4*)(rowp + bj * HALF) = w; } }
.LBB0_920:
	v_lshl_or_b32 v150, s52, 8, v158
	v_lshlrev_b64 v[144:145], 17, v[148:149]
	v_ashrrev_i32_e32 v151, 31, v150
	v_lshl_add_u64 v[144:145], s[10:11], 0, v[144:145]
	s_nop 0
	v_pk_add_f32 v[126:127], v[126:127], v[156:157] op_sel_hi:[1,0]
	v_pk_add_f32 v[124:125], v[124:125], v[156:157] op_sel_hi:[1,0]
	v_pk_add_f32 v[162:163], v[122:123], v[156:157] op_sel_hi:[1,0]
	v_pk_add_f32 v[122:123], v[120:121], v[156:157] op_sel_hi:[1,0]
	v_lshl_add_u64 v[144:145], v[150:151], 1, v[144:145]
	v_cvt_pk_bf16_f32 v120, v124, v125
	v_cvt_pk_bf16_f32 v121, v126, v127
	v_cvt_pk_bf16_f32 v122, v122, v123
	v_cvt_pk_bf16_f32 v123, v162, v163
	global_store_dwordx4 v[144:145], v[120:123], off nt
	v_pk_add_f32 v[118:119], v[118:119], v[156:157] op_sel_hi:[1,0]
	v_pk_add_f32 v[116:117], v[116:117], v[156:157] op_sel_hi:[1,0]
	v_pk_add_f32 v[120:121], v[114:115], v[156:157] op_sel_hi:[1,0]
	v_pk_add_f32 v[114:115], v[112:113], v[156:157] op_sel_hi:[1,0]
	v_cvt_pk_bf16_f32 v112, v116, v117
	v_cvt_pk_bf16_f32 v113, v118, v119
	v_cvt_pk_bf16_f32 v114, v114, v115
	v_cvt_pk_bf16_f32 v115, v120, v121
	s_and_b64 vcc, exec, s[4:5]
	global_store_dwordx4 v[144:145], v[112:115], off offset:256 nt
	v_mov_b32_e32 v154, v231
.LBB0_922:
	s_nop 0
	v_or_b32_e32 v112, 16, v148
	v_ashrrev_i32_e32 v113, 31, v112
	v_lshlrev_b64 v[112:113], 17, v[112:113]
	v_lshl_add_u64 v[112:113], s[10:11], 0, v[112:113]
	s_nop 0
	v_pk_add_f32 v[110:111], v[110:111], v[154:155] op_sel_hi:[1,0]
	v_pk_add_f32 v[108:109], v[108:109], v[154:155] op_sel_hi:[1,0]
	v_pk_add_f32 v[114:115], v[106:107], v[154:155] op_sel_hi:[1,0]
	v_pk_add_f32 v[106:107], v[104:105], v[154:155] op_sel_hi:[1,0]
	v_lshl_add_u64 v[112:113], v[150:151], 1, v[112:113]
	v_cvt_pk_bf16_f32 v104, v108, v109
	v_cvt_pk_bf16_f32 v105, v110, v111
	v_cvt_pk_bf16_f32 v106, v106, v107
	v_cvt_pk_bf16_f32 v107, v114, v115
	global_store_dwordx4 v[112:113], v[104:107], off nt
	v_pk_add_f32 v[102:103], v[102:103], v[154:155] op_sel_hi:[1,0]
	v_pk_add_f32 v[100:101], v[100:101], v[154:155] op_sel_hi:[1,0]
	v_pk_add_f32 v[104:105], v[98:99], v[154:155] op_sel_hi:[1,0]
	v_pk_add_f32 v[98:99], v[96:97], v[154:155] op_sel_hi:[1,0]
	v_cvt_pk_bf16_f32 v96, v100, v101
	v_cvt_pk_bf16_f32 v97, v102, v103
	v_cvt_pk_bf16_f32 v98, v98, v99
	v_cvt_pk_bf16_f32 v99, v104, v105
	global_store_dwordx4 v[112:113], v[96:99], off offset:256 nt
	s_and_b64 vcc, exec, s[4:5]
	s_nop 0
	v_mov_b32_e32 v96, 0
	v_mov_b32_e32 v98, 0
	v_mov_b32_e32 v98, v232
.LBB0_924:
	v_or_b32_e32 v100, 32, v148
	v_ashrrev_i32_e32 v101, 31, v100
	v_lshlrev_b64 v[100:101], 17, v[100:101]
	v_lshl_add_u64 v[100:101], s[10:11], 0, v[100:101]
	s_nop 0
	v_pk_add_f32 v[94:95], v[94:95], v[98:99] op_sel_hi:[1,0]
	v_pk_add_f32 v[92:93], v[92:93], v[98:99] op_sel_hi:[1,0]
	v_pk_add_f32 v[102:103], v[90:91], v[98:99] op_sel_hi:[1,0]
	v_pk_add_f32 v[90:91], v[88:89], v[98:99] op_sel_hi:[1,0]
	v_lshl_add_u64 v[100:101], v[150:151], 1, v[100:101]
	v_cvt_pk_bf16_f32 v88, v92, v93
	v_cvt_pk_bf16_f32 v89, v94, v95
	v_cvt_pk_bf16_f32 v90, v90, v91
	v_cvt_pk_bf16_f32 v91, v102, v103
	global_store_dwordx4 v[100:101], v[88:91], off nt
	v_pk_add_f32 v[86:87], v[86:87], v[98:99] op_sel_hi:[1,0]
	v_pk_add_f32 v[84:85], v[84:85], v[98:99] op_sel_hi:[1,0]
	v_pk_add_f32 v[88:89], v[82:83], v[98:99] op_sel_hi:[1,0]
	v_pk_add_f32 v[82:83], v[80:81], v[98:99] op_sel_hi:[1,0]
	v_cvt_pk_bf16_f32 v80, v84, v85
	v_cvt_pk_bf16_f32 v81, v86, v87
	v_cvt_pk_bf16_f32 v82, v82, v83
	v_cvt_pk_bf16_f32 v83, v88, v89
	s_and_b64 vcc, exec, s[4:5]
	global_store_dwordx4 v[100:101], v[80:83], off offset:256 nt
	v_mov_b32_e32 v96, v233
.LBB0_926:
	s_nop 0
	v_or_b32_e32 v80, 48, v148
	v_ashrrev_i32_e32 v81, 31, v80
	v_lshlrev_b64 v[80:81], 17, v[80:81]
	v_lshl_add_u64 v[80:81], s[10:11], 0, v[80:81]
	s_nop 0
	v_pk_add_f32 v[78:79], v[78:79], v[96:97] op_sel_hi:[1,0]
	v_pk_add_f32 v[76:77], v[76:77], v[96:97] op_sel_hi:[1,0]
	v_pk_add_f32 v[82:83], v[74:75], v[96:97] op_sel_hi:[1,0]
	v_pk_add_f32 v[74:75], v[72:73], v[96:97] op_sel_hi:[1,0]
	v_lshl_add_u64 v[80:81], v[150:151], 1, v[80:81]
	v_cvt_pk_bf16_f32 v72, v76, v77
	v_cvt_pk_bf16_f32 v73, v78, v79
	v_cvt_pk_bf16_f32 v74, v74, v75
	v_cvt_pk_bf16_f32 v75, v82, v83
	global_store_dwordx4 v[80:81], v[72:75], off nt
	v_pk_add_f32 v[70:71], v[70:71], v[96:97] op_sel_hi:[1,0]
	v_pk_add_f32 v[68:69], v[68:69], v[96:97] op_sel_hi:[1,0]
	v_pk_add_f32 v[72:73], v[66:67], v[96:97] op_sel_hi:[1,0]
	v_pk_add_f32 v[66:67], v[64:65], v[96:97] op_sel_hi:[1,0]
	v_cvt_pk_bf16_f32 v64, v68, v69
	v_cvt_pk_bf16_f32 v65, v70, v71
	v_cvt_pk_bf16_f32 v66, v66, v67
	v_cvt_pk_bf16_f32 v67, v72, v73
	global_store_dwordx4 v[80:81], v[64:67], off offset:256 nt
	s_and_b64 vcc, exec, s[4:5]
	s_nop 0
	v_mov_b32_e32 v64, 0
	v_mov_b32_e32 v66, 0
	v_mov_b32_e32 v66, v234
; __device__ __forceinline__ unsigned pk2(float lo, float hi) { f32x2 v = {lo, hi}; bf16x2_t b = __builtin_convertvector(v, bf16x2_t); return __builtin_bit_cast(unsigned, b); }
;     __device__ __forceinline__ void operator()(const f32x4 (&acc)[2][2][4][2], const Unit& u, int wr, int wc, int fr, int fq) const {
;     ...
;             for (int m = 0; m < 4; ++m) { const int row = row0 + ai * HALF + m * 16; const float rb = rowbias ? rowbias[row] : 0.f; bf16_t* rowp = O + (size_t)row * ldc + col0;
; #pragma unroll
;                 for (int bj = 0; bj < 2; ++bj) { const f32x4 v0 = acc[ai][bj][m][0] + rb, v1 = acc[ai][bj][m][1] + rb;
;                     u32x4 w; w.x = pk2(v0[0], v0[1]); w.y = pk2(v0[2], v0[3]); w.z = pk2(v1[0], v1[1]); w.w = pk2(v1[2], v1[3]);
;                     *(u32x4*)(rowp + bj * HALF) = w; } }
.LBB0_928:
	s_nop 0
	v_pk_add_f32 v[60:61], v[60:61], v[66:67] op_sel_hi:[1,0]
	v_pk_add_f32 v[62:63], v[62:63], v[66:67] op_sel_hi:[1,0]
	v_pk_add_f32 v[70:71], v[58:59], v[66:67] op_sel_hi:[1,0]
	v_pk_add_f32 v[58:59], v[56:57], v[66:67] op_sel_hi:[1,0]
	v_cvt_pk_bf16_f32 v56, v60, v61
	v_add_co_u32_e32 v60, vcc, s64, v144
	v_cvt_pk_bf16_f32 v57, v62, v63
	v_cvt_pk_bf16_f32 v58, v58, v59
	v_cvt_pk_bf16_f32 v59, v70, v71
	v_addc_co_u32_e32 v61, vcc, 0, v145, vcc
	global_store_dwordx4 v[60:61], v[56:59], off nt
	v_pk_add_f32 v[54:55], v[54:55], v[66:67] op_sel_hi:[1,0]
	v_pk_add_f32 v[52:53], v[52:53], v[66:67] op_sel_hi:[1,0]
	v_pk_add_f32 v[56:57], v[46:47], v[66:67] op_sel_hi:[1,0]
	v_pk_add_f32 v[46:47], v[44:45], v[66:67] op_sel_hi:[1,0]
	v_lshl_add_u64 v[68:69], v[144:145], 0, s[24:25]
	v_cvt_pk_bf16_f32 v44, v52, v53
	v_cvt_pk_bf16_f32 v45, v54, v55
	v_cvt_pk_bf16_f32 v46, v46, v47
	v_cvt_pk_bf16_f32 v47, v56, v57
	s_and_b64 vcc, exec, s[4:5]
	global_store_dwordx4 v[68:69], v[44:47], off offset:256 nt
	v_mov_b32_e32 v64, v235
.LBB0_930:
	s_nop 0
	v_pk_add_f32 v[46:47], v[50:51], v[64:65] op_sel_hi:[1,0]
	v_pk_add_f32 v[48:49], v[48:49], v[64:65] op_sel_hi:[1,0]
	v_pk_add_f32 v[50:51], v[42:43], v[64:65] op_sel_hi:[1,0]
	v_pk_add_f32 v[42:43], v[40:41], v[64:65] op_sel_hi:[1,0]
	v_cvt_pk_bf16_f32 v41, v46, v47
	v_add_co_u32_e32 v46, vcc, s65, v144
	v_cvt_pk_bf16_f32 v40, v48, v49
	v_cvt_pk_bf16_f32 v42, v42, v43
	v_cvt_pk_bf16_f32 v43, v50, v51
	v_addc_co_u32_e32 v47, vcc, 0, v145, vcc
	global_store_dwordx4 v[46:47], v[40:43], off nt
	v_pk_add_f32 v[38:39], v[38:39], v[64:65] op_sel_hi:[1,0]
	v_pk_add_f32 v[36:37], v[36:37], v[64:65] op_sel_hi:[1,0]
	v_pk_add_f32 v[40:41], v[30:31], v[64:65] op_sel_hi:[1,0]
	v_pk_add_f32 v[30:31], v[28:29], v[64:65] op_sel_hi:[1,0]
	v_lshl_add_u64 v[44:45], v[144:145], 0, s[36:37]
	v_cvt_pk_bf16_f32 v28, v36, v37
	v_cvt_pk_bf16_f32 v29, v38, v39
	v_cvt_pk_bf16_f32 v30, v30, v31
	v_cvt_pk_bf16_f32 v31, v40, v41
	global_store_dwordx4 v[44:45], v[28:31], off offset:256 nt
	s_and_b64 vcc, exec, s[4:5]
	s_nop 0
	v_mov_b32_e32 v28, 0
	v_mov_b32_e32 v30, 0
	v_mov_b32_e32 v30, v236
.LBB0_932:
	s_nop 0
	v_pk_add_f32 v[32:33], v[32:33], v[30:31] op_sel_hi:[1,0]
	v_pk_add_f32 v[34:35], v[34:35], v[30:31] op_sel_hi:[1,0]
	v_pk_add_f32 v[38:39], v[26:27], v[30:31] op_sel_hi:[1,0]
	v_pk_add_f32 v[26:27], v[24:25], v[30:31] op_sel_hi:[1,0]
	v_cvt_pk_bf16_f32 v24, v32, v33
	v_add_co_u32_e32 v32, vcc, s66, v144
	v_cvt_pk_bf16_f32 v25, v34, v35
	v_cvt_pk_bf16_f32 v26, v26, v27
	v_cvt_pk_bf16_f32 v27, v38, v39
	v_addc_co_u32_e32 v33, vcc, 0, v145, vcc
	global_store_dwordx4 v[32:33], v[24:27], off nt
	v_pk_add_f32 v[22:23], v[22:23], v[30:31] op_sel_hi:[1,0]
	v_pk_add_f32 v[20:21], v[20:21], v[30:31] op_sel_hi:[1,0]
	v_pk_add_f32 v[24:25], v[14:15], v[30:31] op_sel_hi:[1,0]
	v_pk_add_f32 v[14:15], v[12:13], v[30:31] op_sel_hi:[1,0]
	v_lshl_add_u64 v[36:37], v[144:145], 0, s[38:39]
	v_cvt_pk_bf16_f32 v12, v20, v21
	v_cvt_pk_bf16_f32 v13, v22, v23
	v_cvt_pk_bf16_f32 v14, v14, v15
	v_cvt_pk_bf16_f32 v15, v24, v25
	s_and_b64 vcc, exec, s[4:5]
	global_store_dwordx4 v[36:37], v[12:15], off offset:256 nt
	v_mov_b32_e32 v28, v237
.LBB0_934:
	s_nop 0
	v_pk_add_f32 v[14:15], v[18:19], v[28:29] op_sel_hi:[1,0]
	v_pk_add_f32 v[16:17], v[16:17], v[28:29] op_sel_hi:[1,0]
	v_pk_add_f32 v[18:19], v[10:11], v[28:29] op_sel_hi:[1,0]
	v_pk_add_f32 v[10:11], v[8:9], v[28:29] op_sel_hi:[1,0]
	v_cvt_pk_bf16_f32 v9, v14, v15
	v_add_co_u32_e32 v14, vcc, s67, v144
	v_cvt_pk_bf16_f32 v8, v16, v17
	v_cvt_pk_bf16_f32 v10, v10, v11
	v_cvt_pk_bf16_f32 v11, v18, v19
	v_addc_co_u32_e32 v15, vcc, 0, v145, vcc
	global_store_dwordx4 v[14:15], v[8:11], off nt
	v_pk_add_f32 v[6:7], v[6:7], v[28:29] op_sel_hi:[1,0]
	v_pk_add_f32 v[4:5], v[4:5], v[28:29] op_sel_hi:[1,0]
	v_pk_add_f32 v[8:9], v[2:3], v[28:29] op_sel_hi:[1,0]
	v_pk_add_f32 v[2:3], v[0:1], v[28:29] op_sel_hi:[1,0]
	v_lshl_add_u64 v[12:13], v[144:145], 0, s[40:41]
	v_cvt_pk_bf16_f32 v0, v4, v5
	v_cvt_pk_bf16_f32 v1, v6, v7
	v_cvt_pk_bf16_f32 v2, v2, v3
	v_cvt_pk_bf16_f32 v3, v8, v9
	s_andn2_b64 vcc, exec, s[0:1]
	s_mov_b64 s[0:1], -1
	global_store_dwordx4 v[12:13], v[0:3], off offset:256 nt
	s_cbranch_vccnz .LBB0_911
	v_lshl_add_u32 v240, s44, 8, v155
	v_ashrrev_i32_e32 v241, 31, v240
	v_lshl_add_u64 v[238:239], v[240:241], 2, s[92:93]
	global_load_dword v230, v[238:239], off
	global_load_dword v231, v[238:239], off offset:64
	global_load_dword v232, v[238:239], off offset:128
	global_load_dword v233, v[238:239], off offset:192
	global_load_dword v234, v[238:239], off offset:512
	global_load_dword v235, v[238:239], off offset:576
	global_load_dword v236, v[238:239], off offset:640
	global_load_dword v237, v[238:239], off offset:704
	s_andn2_b64 vcc, exec, s[8:9]
	s_cbranch_vccnz .LBB0_910
	s_barrier
	s_branch .LBB0_910

; __device__ __forceinline__ unsigned pk2(float lo, float hi) { f32x2 v = {lo, hi}; bf16x2_t b = __builtin_convertvector(v, bf16x2_t); return __builtin_bit_cast(unsigned, b); }
;     __device__ __forceinline__ void operator()(const f32x4 (&acc)[2][2][4][2], const Unit& u, int wr, int wc, int fr, int fq) const {
;         const int row0 = u.pm * BM + wr * 64 + fr; const int col0 = u.pn * BM + wc * 32 + 8 * fq;
;         const float* gp = gate + (size_t)(u.pm >> 5) * 6144;
; #pragma unroll
;         for (int bj = 0; bj < 2; ++bj) { const int c = col0 + bj * HALF;
;             const f32x4 g0 = *(const f32x4*)(gp + c), g1 = *(const f32x4*)(gp + c + 4);
;             const f32x4 b0 = bias ? *(const f32x4*)(bias + c) : (f32x4){0.f, 0.f, 0.f, 0.f}, b1 = bias ? *(const f32x4*)(bias + c + 4) : (f32x4){0.f, 0.f, 0.f, 0.f};
; #pragma unroll
;             for (int ai = 0; ai < 2; ++ai)
; #pragma unroll
;                 for (int m = 0; m < 4; ++m) { const size_t off = (size_t)(row0 + ai * HALF + m * 16) * 1024 + c;
;                     f32x4 x0, x1;
;                     if (BASE_BF16) { const u32x4 v = *(const u32x4*)((const bf16_t*)base + off);
;                         x0 = (f32x4){__uint_as_float(v.x << 16), __uint_as_float(v.x & 0xffff0000u), __uint_as_float(v.y << 16), __uint_as_float(v.y & 0xffff0000u)};
;                         x1 = (f32x4){__uint_as_float(v.z << 16), __uint_as_float(v.z & 0xffff0000u), __uint_as_float(v.w << 16), __uint_as_float(v.w & 0xffff0000u)}; }
;                     else { x0 = *(const f32x4*)((const float*)base + off); x1 = *(const f32x4*)((const float*)base + off + 4); }
;                     x0 = x0 + g0 * (acc[ai][bj][m][0] + b0); x1 = x1 + g1 * (acc[ai][bj][m][1] + b1);
;                     if (OUT_BF16) { u32x4 w; w.x = pk2(x0[0], x0[1]); w.y = pk2(x0[2], x0[3]); w.z = pk2(x1[0], x1[1]); w.w = pk2(x1[2], x1[3]); *(u32x4*)((bf16_t*)out + off) = w; }
;                     else { *(f32x4*)((float*)out + off) = x0; *(f32x4*)((float*)out + off + 4) = x1; } } }
.LBB0_1217:
	v_lshl_add_u32 v172, s48, 8, v178
	v_ashrrev_i32_e32 v173, 31, v172
	v_or_b32_e32 v168, 16, v172
	v_lshlrev_b64 v[146:147], 11, v[172:173]
	v_ashrrev_i32_e32 v169, 31, v168
	v_lshl_add_u64 v[146:147], s[12:13], 0, v[146:147]
	v_lshlrev_b64 v[192:193], 1, v[144:145]
	v_lshlrev_b64 v[168:169], 11, v[168:169]
	v_lshl_add_u64 v[166:167], v[146:147], 0, v[192:193]
	v_lshl_add_u64 v[168:169], s[12:13], 0, v[168:169]
	global_load_dwordx4 v[144:147], v[166:167], off
	v_lshl_add_u64 v[168:169], v[168:169], 0, v[192:193]
	v_or_b32_e32 v170, 32, v172
	global_load_dwordx4 v[184:187], v[168:169], off
	v_ashrrev_i32_e32 v171, 31, v170
	v_lshlrev_b64 v[170:171], 11, v[170:171]
	v_lshl_add_u64 v[170:171], s[12:13], 0, v[170:171]
	v_lshl_add_u64 v[170:171], v[170:171], 0, v[192:193]
	global_load_dwordx4 v[188:191], v[170:171], off
	v_or_b32_e32 v172, 48, v172
	v_ashrrev_i32_e32 v173, 31, v172
	v_lshlrev_b64 v[172:173], 11, v[172:173]
	v_lshl_add_u64 v[172:173], s[12:13], 0, v[172:173]
	v_lshl_add_u64 v[172:173], v[172:173], 0, v[192:193]
	global_load_dwordx4 v[192:195], v[172:173], off
	v_add_co_u32_e32 v208, vcc, s71, v166
	s_waitcnt vmcnt(0)
	v_pk_add_f32 v[126:127], v[126:127], v[142:143]
	v_addc_co_u32_e32 v209, vcc, 0, v167, vcc
	v_add_co_u32_e32 v210, vcc, s72, v166
	v_pk_add_f32 v[124:125], v[124:125], v[140:141]
	v_pk_add_f32 v[122:123], v[122:123], v[134:135]
	v_pk_add_f32 v[120:121], v[120:121], v[132:133]
	v_pk_add_f32 v[196:197], v[118:119], v[142:143]
	v_pk_add_f32 v[198:199], v[116:117], v[140:141]
	v_pk_add_f32 v[200:201], v[114:115], v[134:135]
	v_pk_add_f32 v[202:203], v[112:113], v[132:133]
	v_pk_add_f32 v[204:205], v[110:111], v[142:143]
	v_pk_add_f32 v[206:207], v[108:109], v[140:141]
	v_addc_co_u32_e32 v211, vcc, 0, v167, vcc
	global_load_dwordx4 v[108:111], v[208:209], off
	global_load_dwordx4 v[112:115], v[210:211], off
	v_pk_add_f32 v[106:107], v[106:107], v[134:135]
	v_pk_add_f32 v[104:105], v[104:105], v[132:133]
	v_pk_add_f32 v[102:103], v[102:103], v[142:143]
	v_pk_add_f32 v[100:101], v[100:101], v[140:141]
	v_pk_add_f32 v[98:99], v[98:99], v[134:135]
	v_pk_add_f32 v[96:97], v[96:97], v[132:133]
	v_pk_add_f32 v[94:95], v[94:95], v[142:143]
	v_pk_add_f32 v[92:93], v[92:93], v[140:141]
	v_pk_add_f32 v[90:91], v[90:91], v[134:135]
	v_pk_add_f32 v[88:89], v[88:89], v[132:133]
	v_pk_add_f32 v[86:87], v[86:87], v[142:143]
	v_pk_add_f32 v[84:85], v[84:85], v[140:141]
	v_pk_add_f32 v[82:83], v[82:83], v[134:135]
	v_pk_add_f32 v[80:81], v[80:81], v[132:133]
	v_pk_add_f32 v[78:79], v[78:79], v[142:143]
	v_pk_add_f32 v[76:77], v[76:77], v[140:141]
	v_pk_add_f32 v[74:75], v[74:75], v[134:135]
	v_pk_add_f32 v[72:73], v[72:73], v[132:133]
	v_pk_add_f32 v[70:71], v[70:71], v[142:143]
	v_pk_add_f32 v[68:69], v[68:69], v[140:141]
	v_pk_add_f32 v[66:67], v[66:67], v[134:135]
	v_pk_add_f32 v[64:65], v[64:65], v[132:133]
	v_lshlrev_b32_e32 v116, 16, v144
	v_and_b32_e32 v117, 0xffff0000, v144
	v_lshlrev_b32_e32 v118, 16, v145
	v_and_b32_e32 v119, 0xffff0000, v145
	v_lshlrev_b32_e32 v144, 16, v146
	v_and_b32_e32 v145, 0xffff0000, v146
	v_lshlrev_b32_e32 v146, 16, v147
	v_and_b32_e32 v147, 0xffff0000, v147
	v_pk_fma_f32 v[118:119], v[138:139], v[126:127], v[118:119]
	v_pk_fma_f32 v[116:117], v[136:137], v[124:125], v[116:117]
	v_pk_fma_f32 v[122:123], v[130:131], v[122:123], v[146:147]
	v_pk_fma_f32 v[120:121], v[128:129], v[120:121], v[144:145]
	v_lshlrev_b32_e32 v126, 16, v185
	v_and_b32_e32 v127, 0xffff0000, v185
	v_lshlrev_b32_e32 v124, 16, v184
	v_and_b32_e32 v125, 0xffff0000, v184
	v_lshlrev_b32_e32 v144, 16, v186
	v_and_b32_e32 v145, 0xffff0000, v186
	v_lshlrev_b32_e32 v146, 16, v187
	v_and_b32_e32 v147, 0xffff0000, v187
	v_cvt_pk_bf16_f32 v116, v116, v117
	v_cvt_pk_bf16_f32 v117, v118, v119
	v_cvt_pk_bf16_f32 v118, v120, v121
	v_cvt_pk_bf16_f32 v119, v122, v123
	v_pk_fma_f32 v[120:121], v[138:139], v[196:197], v[126:127]
	v_pk_fma_f32 v[122:123], v[136:137], v[198:199], v[124:125]
	v_pk_fma_f32 v[124:125], v[130:131], v[200:201], v[146:147]
	v_pk_fma_f32 v[126:127], v[128:129], v[202:203], v[144:145]
	global_store_dwordx4 v[166:167], v[116:119], off nt
	v_lshlrev_b32_e32 v184, 16, v188
	v_and_b32_e32 v185, 0xffff0000, v188
	v_cvt_pk_bf16_f32 v117, v120, v121
	v_add_co_u32_e32 v120, vcc, s73, v166
	v_cvt_pk_bf16_f32 v116, v122, v123
	v_cvt_pk_bf16_f32 v118, v126, v127
	v_cvt_pk_bf16_f32 v119, v124, v125
	v_addc_co_u32_e32 v121, vcc, 0, v167, vcc
	v_lshlrev_b32_e32 v186, 16, v189
	v_and_b32_e32 v187, 0xffff0000, v189
	v_lshlrev_b32_e32 v188, 16, v190
	v_and_b32_e32 v189, 0xffff0000, v190
	v_lshlrev_b32_e32 v190, 16, v191
	v_and_b32_e32 v191, 0xffff0000, v191
	global_store_dwordx4 v[168:169], v[116:119], off nt
	global_load_dwordx4 v[116:119], v[120:121], off
	v_pk_fma_f32 v[122:123], v[138:139], v[204:205], v[186:187]
	v_pk_fma_f32 v[124:125], v[136:137], v[206:207], v[184:185]
	v_pk_fma_f32 v[126:127], v[130:131], v[106:107], v[190:191]
	v_pk_fma_f32 v[106:107], v[128:129], v[104:105], v[188:189]
	v_add_co_u32_e32 v144, vcc, s74, v166
	v_cvt_pk_bf16_f32 v104, v124, v125
	v_cvt_pk_bf16_f32 v105, v122, v123
	v_cvt_pk_bf16_f32 v106, v106, v107
	v_cvt_pk_bf16_f32 v107, v126, v127
	v_addc_co_u32_e32 v145, vcc, 0, v167, vcc
	global_store_dwordx4 v[170:171], v[104:107], off nt
	global_load_dwordx4 v[104:107], v[144:145], off
	v_lshlrev_b32_e32 v122, 16, v192
	v_and_b32_e32 v123, 0xffff0000, v192
	v_lshlrev_b32_e32 v124, 16, v193
	v_and_b32_e32 v125, 0xffff0000, v193
	v_lshlrev_b32_e32 v126, 16, v194
	v_and_b32_e32 v127, 0xffff0000, v194
	v_lshlrev_b32_e32 v146, 16, v195
	v_and_b32_e32 v147, 0xffff0000, v195
	v_pk_fma_f32 v[102:103], v[138:139], v[102:103], v[124:125]
	v_pk_fma_f32 v[100:101], v[136:137], v[100:101], v[122:123]
	v_pk_fma_f32 v[122:123], v[130:131], v[98:99], v[146:147]
	v_pk_fma_f32 v[98:99], v[128:129], v[96:97], v[126:127]
	v_cvt_pk_bf16_f32 v96, v100, v101
	v_cvt_pk_bf16_f32 v97, v102, v103
	v_cvt_pk_bf16_f32 v98, v98, v99
	v_cvt_pk_bf16_f32 v99, v122, v123
	global_store_dwordx4 v[172:173], v[96:99], off nt
	s_waitcnt vmcnt(7)
; __device__ __forceinline__ unsigned pk2(float lo, float hi) { f32x2 v = {lo, hi}; bf16x2_t b = __builtin_convertvector(v, bf16x2_t); return __builtin_bit_cast(unsigned, b); }
;     __device__ __forceinline__ void operator()(const f32x4 (&acc)[2][2][4][2], const Unit& u, int wr, int wc, int fr, int fq) const {
;     ...
;                 for (int m = 0; m < 4; ++m) { const size_t off = (size_t)(row0 + ai * HALF + m * 16) * 1024 + c;
;                     f32x4 x0, x1;
;                     if (BASE_BF16) { const u32x4 v = *(const u32x4*)((const bf16_t*)base + off);
;                         x0 = (f32x4){__uint_as_float(v.x << 16), __uint_as_float(v.x & 0xffff0000u), __uint_as_float(v.y << 16), __uint_as_float(v.y & 0xffff0000u)};
;                         x1 = (f32x4){__uint_as_float(v.z << 16), __uint_as_float(v.z & 0xffff0000u), __uint_as_float(v.w << 16), __uint_as_float(v.w & 0xffff0000u)}; }
;                     else { x0 = *(const f32x4*)((const float*)base + off); x1 = *(const f32x4*)((const float*)base + off + 4); }
;                     x0 = x0 + g0 * (acc[ai][bj][m][0] + b0); x1 = x1 + g1 * (acc[ai][bj][m][1] + b1);
;                     if (OUT_BF16) { u32x4 w; w.x = pk2(x0[0], x0[1]); w.y = pk2(x0[2], x0[3]); w.z = pk2(x1[0], x1[1]); w.w = pk2(x1[2], x1[3]); *(u32x4*)((bf16_t*)out + off) = w; }
;                     else { *(f32x4*)((float*)out + off) = x0; *(f32x4*)((float*)out + off + 4) = x1; } } }
	v_lshlrev_b32_e32 v100, 16, v110
	v_and_b32_e32 v101, 0xffff0000, v110
	v_lshlrev_b32_e32 v96, 16, v108
	v_and_b32_e32 v97, 0xffff0000, v108
	v_lshlrev_b32_e32 v98, 16, v109
	v_and_b32_e32 v99, 0xffff0000, v109
	v_lshlrev_b32_e32 v102, 16, v111
	v_and_b32_e32 v103, 0xffff0000, v111
	v_pk_fma_f32 v[94:95], v[138:139], v[94:95], v[98:99]
	v_pk_fma_f32 v[92:93], v[136:137], v[92:93], v[96:97]
	v_pk_fma_f32 v[96:97], v[130:131], v[90:91], v[102:103]
	v_pk_fma_f32 v[90:91], v[128:129], v[88:89], v[100:101]
	v_cvt_pk_bf16_f32 v88, v92, v93
	v_cvt_pk_bf16_f32 v89, v94, v95
	v_cvt_pk_bf16_f32 v90, v90, v91
	v_cvt_pk_bf16_f32 v91, v96, v97
	global_store_dwordx4 v[208:209], v[88:91], off nt
	s_waitcnt vmcnt(7)
	v_lshlrev_b32_e32 v92, 16, v114
	v_and_b32_e32 v93, 0xffff0000, v114
	v_lshlrev_b32_e32 v88, 16, v112
	v_and_b32_e32 v89, 0xffff0000, v112
	v_lshlrev_b32_e32 v90, 16, v113
	v_and_b32_e32 v91, 0xffff0000, v113
	v_lshlrev_b32_e32 v94, 16, v115
	v_and_b32_e32 v95, 0xffff0000, v115
	v_pk_fma_f32 v[86:87], v[138:139], v[86:87], v[90:91]
	v_pk_fma_f32 v[84:85], v[136:137], v[84:85], v[88:89]
	v_pk_fma_f32 v[88:89], v[130:131], v[82:83], v[94:95]
	v_pk_fma_f32 v[82:83], v[128:129], v[80:81], v[92:93]
	v_cvt_pk_bf16_f32 v80, v84, v85
	v_cvt_pk_bf16_f32 v81, v86, v87
	v_cvt_pk_bf16_f32 v82, v82, v83
	v_cvt_pk_bf16_f32 v83, v88, v89
	global_store_dwordx4 v[210:211], v[80:83], off nt
	s_and_b64 vcc, exec, s[4:5]
	s_waitcnt vmcnt(5)
	v_lshlrev_b32_e32 v84, 16, v118
	v_lshlrev_b32_e32 v80, 16, v116
	v_and_b32_e32 v81, 0xffff0000, v116
	v_lshlrev_b32_e32 v82, 16, v117
	v_and_b32_e32 v83, 0xffff0000, v117
	v_and_b32_e32 v85, 0xffff0000, v118
	v_lshlrev_b32_e32 v86, 16, v119
	v_and_b32_e32 v87, 0xffff0000, v119
	v_pk_fma_f32 v[78:79], v[138:139], v[78:79], v[82:83]
	v_pk_fma_f32 v[76:77], v[136:137], v[76:77], v[80:81]
	v_pk_fma_f32 v[80:81], v[130:131], v[74:75], v[86:87]
	v_pk_fma_f32 v[74:75], v[128:129], v[72:73], v[84:85]
	v_cvt_pk_bf16_f32 v72, v76, v77
	v_cvt_pk_bf16_f32 v73, v78, v79
	v_cvt_pk_bf16_f32 v74, v74, v75
	v_cvt_pk_bf16_f32 v75, v80, v81
	global_store_dwordx4 v[120:121], v[72:75], off nt
	s_waitcnt vmcnt(4)
	v_lshlrev_b32_e32 v76, 16, v106
	v_and_b32_e32 v77, 0xffff0000, v106
	v_lshlrev_b32_e32 v72, 16, v104
	v_and_b32_e32 v73, 0xffff0000, v104
	v_lshlrev_b32_e32 v74, 16, v105
	v_and_b32_e32 v75, 0xffff0000, v105
	v_lshlrev_b32_e32 v78, 16, v107
	v_and_b32_e32 v79, 0xffff0000, v107
	v_pk_fma_f32 v[70:71], v[138:139], v[70:71], v[74:75]
	v_pk_fma_f32 v[68:69], v[136:137], v[68:69], v[72:73]
	v_pk_fma_f32 v[72:73], v[130:131], v[66:67], v[78:79]
	v_pk_fma_f32 v[66:67], v[128:129], v[64:65], v[76:77]
	v_cvt_pk_bf16_f32 v64, v68, v69
	v_cvt_pk_bf16_f32 v65, v70, v71
	v_cvt_pk_bf16_f32 v66, v66, v67
	v_cvt_pk_bf16_f32 v67, v72, v73
	global_store_dwordx4 v[144:145], v[64:67], off nt
	global_load_dwordx4 v[64:67], v[176:177], off offset:528
	s_nop 0
	global_load_dwordx4 v[72:75], v[176:177], off offset:512
	v_mov_b32_e32 v68, 0
	v_mov_b32_e32 v76, 0
	v_mov_b32_e32 v77, 0
	v_mov_b32_e32 v78, 0
	v_mov_b32_e32 v79, 0
	s_cbranch_vccnz .LBB0_1219
	global_load_dwordx4 v[76:79], v[174:175], off offset:512

;     __device__ __forceinline__ void operator()(const f32x4 (&acc)[2][2][4][2], const Unit& u, int wr, int wc, int fr, int fq) const {
;     ...
;             const f32x4 b0 = bias ? *(const f32x4*)(bias + c) : (f32x4){0.f, 0.f, 0.f, 0.f}, b1 = bias ? *(const f32x4*)(bias + c + 4) : (f32x4){0.f, 0.f, 0.f, 0.f};
; #pragma unroll
;             for (int ai = 0; ai < 2; ++ai)
; #pragma unroll
;                 for (int m = 0; m < 4; ++m) { const size_t off = (size_t)(row0 + ai * HALF + m * 16) * 1024 + c;
;                     f32x4 x0, x1;
;                     if (BASE_BF16) { const u32x4 v = *(const u32x4*)((const bf16_t*)base + off);
;                         x0 = (f32x4){__uint_as_float(v.x << 16), __uint_as_float(v.x & 0xffff0000u), __uint_as_float(v.y << 16), __uint_as_float(v.y & 0xffff0000u)};
;                         x1 = (f32x4){__uint_as_float(v.z << 16), __uint_as_float(v.z & 0xffff0000u), __uint_as_float(v.w << 16), __uint_as_float(v.w & 0xffff0000u)}; }
;                     else { x0 = *(const f32x4*)((const float*)base + off); x1 = *(const f32x4*)((const float*)base + off + 4); }
;                     x0 = x0 + g0 * (acc[ai][bj][m][0] + b0); x1 = x1 + g1 * (acc[ai][bj][m][1] + b1);
.LBB0_1221:
	global_load_dwordx4 v[80:83], v[166:167], off offset:256
	global_load_dwordx4 v[84:87], v[168:169], off offset:256
	global_load_dwordx4 v[96:99], v[170:171], off offset:256
	global_load_dwordx4 v[100:103], v[172:173], off offset:256
	v_lshl_add_u64 v[94:95], v[166:167], 0, s[8:9]
	s_waitcnt vmcnt(4)
	v_pk_add_f32 v[108:109], v[50:51], v[70:71]
	v_pk_add_f32 v[110:111], v[48:49], v[68:69]
	global_load_dwordx4 v[48:51], v[94:95], off offset:256
	v_lshl_add_u64 v[92:93], v[166:167], 0, s[24:25]
	v_lshl_add_u64 v[90:91], v[166:167], 0, s[36:37]
	v_lshl_add_u64 v[88:89], v[166:167], 0, s[38:39]
	v_pk_add_f32 v[104:105], v[54:55], v[78:79]
	v_pk_add_f32 v[106:107], v[52:53], v[76:77]
	v_pk_add_f32 v[112:113], v[44:45], v[76:77]
	v_pk_add_f32 v[114:115], v[42:43], v[70:71]
	v_pk_add_f32 v[116:117], v[40:41], v[68:69]
	v_pk_add_f32 v[118:119], v[38:39], v[78:79]
	global_load_dwordx4 v[38:41], v[92:93], off offset:256
	global_load_dwordx4 v[42:45], v[90:91], off offset:256
	global_load_dwordx4 v[52:55], v[88:89], off offset:256
	v_pk_add_f32 v[62:63], v[62:63], v[78:79]
	v_pk_add_f32 v[60:61], v[60:61], v[76:77]
	v_pk_add_f32 v[58:59], v[58:59], v[70:71]
	v_pk_add_f32 v[56:57], v[56:57], v[68:69]
	v_pk_add_f32 v[46:47], v[46:47], v[78:79]
	v_pk_add_f32 v[36:37], v[36:37], v[76:77]
	v_pk_add_f32 v[34:35], v[34:35], v[70:71]
	v_pk_add_f32 v[32:33], v[32:33], v[68:69]
	v_pk_add_f32 v[30:31], v[30:31], v[78:79]
	v_pk_add_f32 v[28:29], v[28:29], v[76:77]
	v_pk_add_f32 v[26:27], v[26:27], v[70:71]
	v_pk_add_f32 v[24:25], v[24:25], v[68:69]
	v_pk_add_f32 v[22:23], v[22:23], v[78:79]
	v_pk_add_f32 v[20:21], v[20:21], v[76:77]
	v_pk_add_f32 v[18:19], v[18:19], v[70:71]
	v_pk_add_f32 v[16:17], v[16:17], v[68:69]
	v_pk_add_f32 v[14:15], v[14:15], v[78:79]
	v_pk_add_f32 v[12:13], v[12:13], v[76:77]
	v_pk_add_f32 v[10:11], v[10:11], v[70:71]
	v_pk_add_f32 v[8:9], v[8:9], v[68:69]
	v_pk_add_f32 v[6:7], v[6:7], v[78:79]
	v_pk_add_f32 v[4:5], v[4:5], v[76:77]
	v_pk_add_f32 v[2:3], v[2:3], v[70:71]
	v_pk_add_f32 v[0:1], v[0:1], v[68:69]
	s_andn2_b64 vcc, exec, s[0:1]
	s_mov_b64 s[0:1], -1
	s_waitcnt vmcnt(7)
	v_lshlrev_b32_e32 v120, 16, v80
	v_and_b32_e32 v121, 0xffff0000, v80
	v_lshlrev_b32_e32 v80, 16, v81
	v_and_b32_e32 v81, 0xffff0000, v81
	v_lshlrev_b32_e32 v122, 16, v82
	v_and_b32_e32 v123, 0xffff0000, v82
	v_lshlrev_b32_e32 v82, 16, v83
	v_and_b32_e32 v83, 0xffff0000, v83
	s_waitcnt vmcnt(6)
	v_lshlrev_b32_e32 v124, 16, v84
	v_and_b32_e32 v125, 0xffff0000, v84
	v_lshlrev_b32_e32 v84, 16, v85
	v_and_b32_e32 v85, 0xffff0000, v85
	v_lshlrev_b32_e32 v126, 16, v86
	v_and_b32_e32 v127, 0xffff0000, v86
	v_lshlrev_b32_e32 v86, 16, v87
	v_and_b32_e32 v87, 0xffff0000, v87
	s_waitcnt vmcnt(5)
	v_lshlrev_b32_e32 v128, 16, v96
	v_and_b32_e32 v129, 0xffff0000, v96
	v_lshlrev_b32_e32 v96, 16, v97
	v_and_b32_e32 v97, 0xffff0000, v97
	v_lshlrev_b32_e32 v130, 16, v98
	v_and_b32_e32 v131, 0xffff0000, v98
	v_lshlrev_b32_e32 v98, 16, v99
	v_and_b32_e32 v99, 0xffff0000, v99
	v_pk_fma_f32 v[62:63], v[74:75], v[62:63], v[80:81]
	v_pk_fma_f32 v[60:61], v[72:73], v[60:61], v[120:121]
	v_pk_fma_f32 v[80:81], v[66:67], v[58:59], v[82:83]
	v_pk_fma_f32 v[58:59], v[64:65], v[56:57], v[122:123]
	s_waitcnt vmcnt(4)
; __device__ __forceinline__ unsigned pk2(float lo, float hi) { f32x2 v = {lo, hi}; bf16x2_t b = __builtin_convertvector(v, bf16x2_t); return __builtin_bit_cast(unsigned, b); }
;     __device__ __forceinline__ void operator()(const f32x4 (&acc)[2][2][4][2], const Unit& u, int wr, int wc, int fr, int fq) const {
;     ...
;                 for (int m = 0; m < 4; ++m) { const size_t off = (size_t)(row0 + ai * HALF + m * 16) * 1024 + c;
;                     f32x4 x0, x1;
;                     if (BASE_BF16) { const u32x4 v = *(const u32x4*)((const bf16_t*)base + off);
;                         x0 = (f32x4){__uint_as_float(v.x << 16), __uint_as_float(v.x & 0xffff0000u), __uint_as_float(v.y << 16), __uint_as_float(v.y & 0xffff0000u)};
;                         x1 = (f32x4){__uint_as_float(v.z << 16), __uint_as_float(v.z & 0xffff0000u), __uint_as_float(v.w << 16), __uint_as_float(v.w & 0xffff0000u)}; }
;                     else { x0 = *(const f32x4*)((const float*)base + off); x1 = *(const f32x4*)((const float*)base + off + 4); }
;                     x0 = x0 + g0 * (acc[ai][bj][m][0] + b0); x1 = x1 + g1 * (acc[ai][bj][m][1] + b1);
;                     if (OUT_BF16) { u32x4 w; w.x = pk2(x0[0], x0[1]); w.y = pk2(x0[2], x0[3]); w.z = pk2(x1[0], x1[1]); w.w = pk2(x1[2], x1[3]); *(u32x4*)((bf16_t*)out + off) = w; }
;                     else { *(f32x4*)((float*)out + off) = x0; *(f32x4*)((float*)out + off + 4) = x1; } } }
	v_lshlrev_b32_e32 v132, 16, v100
	v_and_b32_e32 v133, 0xffff0000, v100
	v_lshlrev_b32_e32 v100, 16, v101
	v_and_b32_e32 v101, 0xffff0000, v101
	v_lshlrev_b32_e32 v134, 16, v102
	v_and_b32_e32 v135, 0xffff0000, v102
	v_lshlrev_b32_e32 v102, 16, v103
	v_and_b32_e32 v103, 0xffff0000, v103
	v_pk_fma_f32 v[82:83], v[74:75], v[104:105], v[84:85]
	v_pk_fma_f32 v[84:85], v[72:73], v[106:107], v[124:125]
	v_pk_fma_f32 v[86:87], v[66:67], v[108:109], v[86:87]
	v_pk_fma_f32 v[104:105], v[64:65], v[110:111], v[126:127]
	v_pk_fma_f32 v[46:47], v[74:75], v[46:47], v[96:97]
	v_pk_fma_f32 v[96:97], v[72:73], v[112:113], v[128:129]
	v_pk_fma_f32 v[98:99], v[66:67], v[114:115], v[98:99]
	v_pk_fma_f32 v[106:107], v[64:65], v[116:117], v[130:131]
	v_cvt_pk_bf16_f32 v56, v60, v61
	v_cvt_pk_bf16_f32 v57, v62, v63
	v_cvt_pk_bf16_f32 v58, v58, v59
	v_cvt_pk_bf16_f32 v59, v80, v81
	v_cvt_pk_bf16_f32 v60, v84, v85
	v_cvt_pk_bf16_f32 v61, v82, v83
	v_cvt_pk_bf16_f32 v62, v104, v105
	v_cvt_pk_bf16_f32 v63, v86, v87
	v_cvt_pk_bf16_f32 v80, v96, v97
	v_cvt_pk_bf16_f32 v81, v46, v47
	v_cvt_pk_bf16_f32 v82, v106, v107
	v_cvt_pk_bf16_f32 v83, v98, v99
	global_store_dwordx4 v[166:167], v[56:59], off offset:256 nt
	global_store_dwordx4 v[168:169], v[60:63], off offset:256 nt
	global_store_dwordx4 v[170:171], v[80:83], off offset:256 nt
	v_pk_fma_f32 v[46:47], v[74:75], v[118:119], v[100:101]
	v_pk_fma_f32 v[36:37], v[72:73], v[36:37], v[132:133]
	v_pk_fma_f32 v[56:57], v[66:67], v[34:35], v[102:103]
	v_pk_fma_f32 v[34:35], v[64:65], v[32:33], v[134:135]
	v_cvt_pk_bf16_f32 v32, v36, v37
	v_cvt_pk_bf16_f32 v33, v46, v47
	v_cvt_pk_bf16_f32 v34, v34, v35
	v_cvt_pk_bf16_f32 v35, v56, v57
	global_store_dwordx4 v[172:173], v[32:35], off offset:256 nt
	s_waitcnt vmcnt(7)
	v_lshlrev_b32_e32 v36, 16, v50
	v_and_b32_e32 v37, 0xffff0000, v50
	v_lshlrev_b32_e32 v32, 16, v48
	v_and_b32_e32 v33, 0xffff0000, v48
	v_lshlrev_b32_e32 v34, 16, v49
	v_and_b32_e32 v35, 0xffff0000, v49
	v_lshlrev_b32_e32 v46, 16, v51
	v_and_b32_e32 v47, 0xffff0000, v51
	v_pk_fma_f32 v[30:31], v[74:75], v[30:31], v[34:35]
	v_pk_fma_f32 v[28:29], v[72:73], v[28:29], v[32:33]
	v_pk_fma_f32 v[32:33], v[66:67], v[26:27], v[46:47]
	v_pk_fma_f32 v[26:27], v[64:65], v[24:25], v[36:37]
	v_cvt_pk_bf16_f32 v24, v28, v29
	v_cvt_pk_bf16_f32 v25, v30, v31
	v_cvt_pk_bf16_f32 v26, v26, v27
	v_cvt_pk_bf16_f32 v27, v32, v33
	global_store_dwordx4 v[94:95], v[24:27], off offset:256 nt
	s_waitcnt vmcnt(7)
	v_lshlrev_b32_e32 v28, 16, v40
	v_and_b32_e32 v29, 0xffff0000, v40
	v_lshlrev_b32_e32 v24, 16, v38
	v_and_b32_e32 v25, 0xffff0000, v38
	v_lshlrev_b32_e32 v26, 16, v39
	v_and_b32_e32 v27, 0xffff0000, v39
	v_lshlrev_b32_e32 v30, 16, v41
	v_and_b32_e32 v31, 0xffff0000, v41
	v_pk_fma_f32 v[22:23], v[74:75], v[22:23], v[26:27]
	v_pk_fma_f32 v[20:21], v[72:73], v[20:21], v[24:25]
	v_pk_fma_f32 v[24:25], v[66:67], v[18:19], v[30:31]
	v_pk_fma_f32 v[18:19], v[64:65], v[16:17], v[28:29]
	v_cvt_pk_bf16_f32 v16, v20, v21
	v_cvt_pk_bf16_f32 v17, v22, v23
	v_cvt_pk_bf16_f32 v18, v18, v19
	v_cvt_pk_bf16_f32 v19, v24, v25
	global_store_dwordx4 v[92:93], v[16:19], off offset:256 nt
	s_waitcnt vmcnt(7)
	v_lshlrev_b32_e32 v20, 16, v44
	v_and_b32_e32 v21, 0xffff0000, v44
	v_lshlrev_b32_e32 v16, 16, v42
	v_and_b32_e32 v17, 0xffff0000, v42
	v_lshlrev_b32_e32 v18, 16, v43
	v_and_b32_e32 v19, 0xffff0000, v43
	v_lshlrev_b32_e32 v22, 16, v45
	v_and_b32_e32 v23, 0xffff0000, v45
	v_pk_fma_f32 v[14:15], v[74:75], v[14:15], v[18:19]
	v_pk_fma_f32 v[12:13], v[72:73], v[12:13], v[16:17]
	v_pk_fma_f32 v[16:17], v[66:67], v[10:11], v[22:23]
	v_pk_fma_f32 v[10:11], v[64:65], v[8:9], v[20:21]
	v_cvt_pk_bf16_f32 v8, v12, v13
	v_cvt_pk_bf16_f32 v9, v14, v15
	v_cvt_pk_bf16_f32 v10, v10, v11
	v_cvt_pk_bf16_f32 v11, v16, v17
	global_store_dwordx4 v[90:91], v[8:11], off offset:256 nt
	s_waitcnt vmcnt(7)
	v_lshlrev_b32_e32 v12, 16, v54
	v_and_b32_e32 v13, 0xffff0000, v54
	v_lshlrev_b32_e32 v8, 16, v52
	v_and_b32_e32 v9, 0xffff0000, v52
	v_lshlrev_b32_e32 v10, 16, v53
	v_and_b32_e32 v11, 0xffff0000, v53
	v_lshlrev_b32_e32 v14, 16, v55
	v_and_b32_e32 v15, 0xffff0000, v55
	v_pk_fma_f32 v[6:7], v[74:75], v[6:7], v[10:11]
	v_pk_fma_f32 v[4:5], v[72:73], v[4:5], v[8:9]
	v_pk_fma_f32 v[8:9], v[66:67], v[2:3], v[14:15]
	v_pk_fma_f32 v[2:3], v[64:65], v[0:1], v[12:13]
	v_cvt_pk_bf16_f32 v0, v4, v5
	v_cvt_pk_bf16_f32 v1, v6, v7
	v_cvt_pk_bf16_f32 v2, v2, v3
	v_cvt_pk_bf16_f32 v3, v8, v9
	global_store_dwordx4 v[88:89], v[0:3], off offset:256 nt
	s_cbranch_vccnz .LBB0_1202
	s_andn2_b64 vcc, exec, s[10:11]
	s_cbranch_vccnz .LBB0_1201
	s_barrier
	s_branch .LBB0_1201
